# GEMM epilogue bf16 tile stores (dwordx4) as write-through sc0 sc1: nothing dirty for the grid barrier's L2 write-back
# baseline (speedup 1.0000x reference)
.LBB0_153:
	s_and_b64 s[10:11], s[10:11], exec
	s_mov_b32 s10, 0x4200000
	s_cselect_b32 s10, s10, 0x6300000
	s_cmp_gt_u32 s56, 1
	s_cselect_b32 s10, s10, 0x2100000
	s_add_u32 s10, s30, s10
	s_addc_u32 s11, s31, 0
	v_lshlrev_b32_e32 v174, 1, v142
	v_ashrrev_i32_e32 v209, 31, v208
	v_lshl_add_u64 v[138:139], s[10:11], 0, v[174:175]
	v_lshlrev_b64 v[140:141], 10, v[208:209]
	v_lshl_add_u64 v[140:141], v[138:139], 0, v[140:141]
	v_cvt_pk_bf16_f32 v130, v130, v131
	v_cvt_pk_bf16_f32 v131, v132, v133
	v_cvt_pk_bf16_f32 v132, v134, v135
	v_cvt_pk_bf16_f32 v133, v136, v137
	global_store_dwordx4 v[140:141], v[130:133], off sc0 sc1
	s_andn2_b64 vcc, exec, s[12:13]
	s_nop 0
	v_cndmask_b32_e64 v130, 0, 1, s[12:13]
	v_cmp_ne_u32_e64 s[10:11], 1, v130
	s_mov_b64 s[12:13], -1
	s_cbranch_vccnz .LBB0_155
	v_mul_f32_e32 v130, 0xbfb8aa3b, v118
	v_mul_f32_e32 v131, 0xbfb8aa3b, v119
	v_mul_f32_e32 v132, 0xbfb8aa3b, v120
	v_mul_f32_e32 v133, 0xbfb8aa3b, v121
	v_mul_f32_e32 v134, 0xbfb8aa3b, v114
	v_mul_f32_e32 v135, 0xbfb8aa3b, v115
	v_mul_f32_e32 v136, 0xbfb8aa3b, v116
	v_mul_f32_e32 v137, 0xbfb8aa3b, v117
	v_exp_f32_e32 v130, v130
	v_exp_f32_e32 v131, v131
	v_exp_f32_e32 v132, v132
	v_exp_f32_e32 v133, v133
	v_exp_f32_e32 v134, v134
	v_exp_f32_e32 v135, v135
	v_exp_f32_e32 v136, v136
	v_exp_f32_e32 v137, v137
	v_add_f32_e32 v130, 1.0, v130
	v_add_f32_e32 v131, 1.0, v131
	v_add_f32_e32 v132, 1.0, v132
	v_add_f32_e32 v133, 1.0, v133
	v_add_f32_e32 v134, 1.0, v134
	v_add_f32_e32 v135, 1.0, v135
	v_add_f32_e32 v136, 1.0, v136
	v_add_f32_e32 v137, 1.0, v137
	v_rcp_f32_e32 v130, v130
	v_rcp_f32_e32 v131, v131
	v_rcp_f32_e32 v132, v132
	v_rcp_f32_e32 v133, v133
	v_rcp_f32_e32 v134, v134
	v_rcp_f32_e32 v136, v136
	v_rcp_f32_e32 v137, v137
	v_rcp_f32_e32 v135, v135
	v_pk_mul_f32 v[132:133], v[120:121], v[132:133]
	v_pk_mul_f32 v[130:131], v[118:119], v[130:131]
	v_pk_mul_f32 v[136:137], v[116:117], v[136:137]
	v_pk_mul_f32 v[134:135], v[114:115], v[134:135]
	s_mov_b64 s[12:13], 0

.LBB0_157:
	v_cvt_pk_bf16_f32 v130, v130, v131
	v_cvt_pk_bf16_f32 v131, v132, v133
	s_nop 0
	v_cvt_pk_bf16_f32 v132, v134, v135
	v_cvt_pk_bf16_f32 v133, v136, v137
	s_and_b64 vcc, exec, s[10:11]
	s_mov_b64 s[12:13], -1
	global_store_dwordx4 v[140:141], v[130:133], off offset:256 sc0 sc1
	s_cbranch_vccnz .LBB0_159
	s_nop 0
	v_mul_f32_e32 v130, 0xbfb8aa3b, v110
	v_mul_f32_e32 v131, 0xbfb8aa3b, v111
	v_mul_f32_e32 v132, 0xbfb8aa3b, v112
	v_mul_f32_e32 v133, 0xbfb8aa3b, v113
	v_mul_f32_e32 v134, 0xbfb8aa3b, v106
	v_mul_f32_e32 v135, 0xbfb8aa3b, v107
	v_mul_f32_e32 v136, 0xbfb8aa3b, v108
	v_mul_f32_e32 v137, 0xbfb8aa3b, v109
	v_exp_f32_e32 v130, v130
	v_exp_f32_e32 v131, v131
	v_exp_f32_e32 v132, v132
	v_exp_f32_e32 v133, v133
	v_exp_f32_e32 v134, v134
	v_exp_f32_e32 v135, v135
	v_exp_f32_e32 v136, v136
	v_exp_f32_e32 v137, v137
	v_add_f32_e32 v130, 1.0, v130
	v_add_f32_e32 v131, 1.0, v131
	v_add_f32_e32 v132, 1.0, v132
	v_add_f32_e32 v133, 1.0, v133
	v_add_f32_e32 v134, 1.0, v134
	v_add_f32_e32 v135, 1.0, v135
	v_add_f32_e32 v136, 1.0, v136
	v_add_f32_e32 v137, 1.0, v137
	v_rcp_f32_e32 v130, v130
	v_rcp_f32_e32 v131, v131
	v_rcp_f32_e32 v132, v132
	v_rcp_f32_e32 v133, v133
	v_rcp_f32_e32 v134, v134
	v_rcp_f32_e32 v136, v136
	v_rcp_f32_e32 v137, v137
	v_rcp_f32_e32 v135, v135
	v_pk_mul_f32 v[132:133], v[112:113], v[132:133]
	v_pk_mul_f32 v[130:131], v[110:111], v[130:131]
	v_pk_mul_f32 v[136:137], v[108:109], v[136:137]
	v_pk_mul_f32 v[134:135], v[106:107], v[134:135]
	s_mov_b64 s[12:13], 0

.LBB0_161:
	v_or_b32_e32 v140, 16, v208
	v_ashrrev_i32_e32 v141, 31, v140
	v_lshlrev_b64 v[140:141], 10, v[140:141]
	v_lshl_add_u64 v[140:141], v[138:139], 0, v[140:141]
	v_cvt_pk_bf16_f32 v130, v130, v131
	v_cvt_pk_bf16_f32 v131, v132, v133
	v_cvt_pk_bf16_f32 v132, v134, v135
	v_cvt_pk_bf16_f32 v133, v136, v137
	s_and_b64 vcc, exec, s[10:11]
	s_mov_b64 s[12:13], -1
	global_store_dwordx4 v[140:141], v[130:133], off sc0 sc1
	s_cbranch_vccnz .LBB0_163
	s_nop 0
	v_mul_f32_e32 v130, 0xbfb8aa3b, v102
	v_mul_f32_e32 v131, 0xbfb8aa3b, v103
	v_mul_f32_e32 v132, 0xbfb8aa3b, v104
	v_mul_f32_e32 v133, 0xbfb8aa3b, v105
	v_mul_f32_e32 v134, 0xbfb8aa3b, v98
	v_mul_f32_e32 v135, 0xbfb8aa3b, v99
	v_mul_f32_e32 v136, 0xbfb8aa3b, v100
	v_mul_f32_e32 v137, 0xbfb8aa3b, v101
	v_exp_f32_e32 v130, v130
	v_exp_f32_e32 v131, v131
	v_exp_f32_e32 v132, v132
	v_exp_f32_e32 v133, v133
	v_exp_f32_e32 v134, v134
	v_exp_f32_e32 v135, v135
	v_exp_f32_e32 v136, v136
	v_exp_f32_e32 v137, v137
	v_add_f32_e32 v130, 1.0, v130
	v_add_f32_e32 v131, 1.0, v131
	v_add_f32_e32 v132, 1.0, v132
	v_add_f32_e32 v133, 1.0, v133
	v_add_f32_e32 v134, 1.0, v134
	v_add_f32_e32 v135, 1.0, v135
	v_add_f32_e32 v136, 1.0, v136
	v_add_f32_e32 v137, 1.0, v137
	v_rcp_f32_e32 v130, v130
	v_rcp_f32_e32 v131, v131
	v_rcp_f32_e32 v132, v132
	v_rcp_f32_e32 v133, v133
	v_rcp_f32_e32 v134, v134
	v_rcp_f32_e32 v136, v136
	v_rcp_f32_e32 v137, v137
	v_rcp_f32_e32 v135, v135
	v_pk_mul_f32 v[132:133], v[104:105], v[132:133]
	v_pk_mul_f32 v[130:131], v[102:103], v[130:131]
	v_pk_mul_f32 v[136:137], v[100:101], v[136:137]
	v_pk_mul_f32 v[134:135], v[98:99], v[134:135]
	s_mov_b64 s[12:13], 0

.LBB0_165:
	v_cvt_pk_bf16_f32 v130, v130, v131
	v_cvt_pk_bf16_f32 v131, v132, v133
	s_nop 0
	v_cvt_pk_bf16_f32 v132, v134, v135
	v_cvt_pk_bf16_f32 v133, v136, v137
	s_and_b64 vcc, exec, s[10:11]
	s_mov_b64 s[12:13], -1
	global_store_dwordx4 v[140:141], v[130:133], off offset:256 sc0 sc1
	s_cbranch_vccnz .LBB0_167
	s_nop 0
	v_mul_f32_e32 v130, 0xbfb8aa3b, v94
	v_mul_f32_e32 v131, 0xbfb8aa3b, v95
	v_mul_f32_e32 v132, 0xbfb8aa3b, v96
	v_mul_f32_e32 v133, 0xbfb8aa3b, v97
	v_mul_f32_e32 v134, 0xbfb8aa3b, v90
	v_mul_f32_e32 v135, 0xbfb8aa3b, v91
	v_mul_f32_e32 v136, 0xbfb8aa3b, v92
	v_mul_f32_e32 v137, 0xbfb8aa3b, v93
	v_exp_f32_e32 v130, v130
	v_exp_f32_e32 v131, v131
	v_exp_f32_e32 v132, v132
	v_exp_f32_e32 v133, v133
	v_exp_f32_e32 v134, v134
	v_exp_f32_e32 v135, v135
	v_exp_f32_e32 v136, v136
	v_exp_f32_e32 v137, v137
	v_add_f32_e32 v130, 1.0, v130
	v_add_f32_e32 v131, 1.0, v131
	v_add_f32_e32 v132, 1.0, v132
	v_add_f32_e32 v133, 1.0, v133
	v_add_f32_e32 v134, 1.0, v134
	v_add_f32_e32 v135, 1.0, v135
	v_add_f32_e32 v136, 1.0, v136
	v_add_f32_e32 v137, 1.0, v137
	v_rcp_f32_e32 v130, v130
	v_rcp_f32_e32 v131, v131
	v_rcp_f32_e32 v132, v132
	v_rcp_f32_e32 v133, v133
	v_rcp_f32_e32 v134, v134
	v_rcp_f32_e32 v136, v136
	v_rcp_f32_e32 v137, v137
	v_rcp_f32_e32 v135, v135
	v_pk_mul_f32 v[132:133], v[96:97], v[132:133]
	v_pk_mul_f32 v[130:131], v[94:95], v[130:131]
	v_pk_mul_f32 v[136:137], v[92:93], v[136:137]
	v_pk_mul_f32 v[134:135], v[90:91], v[134:135]
	s_mov_b64 s[12:13], 0

.LBB0_169:
	v_or_b32_e32 v140, 32, v208
	v_ashrrev_i32_e32 v141, 31, v140
	v_lshlrev_b64 v[140:141], 10, v[140:141]
	v_lshl_add_u64 v[140:141], v[138:139], 0, v[140:141]
	v_cvt_pk_bf16_f32 v130, v130, v131
	v_cvt_pk_bf16_f32 v131, v132, v133
	v_cvt_pk_bf16_f32 v132, v134, v135
	v_cvt_pk_bf16_f32 v133, v136, v137
	s_and_b64 vcc, exec, s[10:11]
	s_mov_b64 s[12:13], -1
	global_store_dwordx4 v[140:141], v[130:133], off sc0 sc1
	s_cbranch_vccnz .LBB0_171
	s_nop 0
	v_mul_f32_e32 v130, 0xbfb8aa3b, v86
	v_mul_f32_e32 v131, 0xbfb8aa3b, v87
	v_mul_f32_e32 v132, 0xbfb8aa3b, v88
	v_mul_f32_e32 v133, 0xbfb8aa3b, v89
	v_mul_f32_e32 v134, 0xbfb8aa3b, v82
	v_mul_f32_e32 v135, 0xbfb8aa3b, v83
	v_mul_f32_e32 v136, 0xbfb8aa3b, v84
	v_mul_f32_e32 v137, 0xbfb8aa3b, v85
	v_exp_f32_e32 v130, v130
	v_exp_f32_e32 v131, v131
	v_exp_f32_e32 v132, v132
	v_exp_f32_e32 v133, v133
	v_exp_f32_e32 v134, v134
	v_exp_f32_e32 v135, v135
	v_exp_f32_e32 v136, v136
	v_exp_f32_e32 v137, v137
	v_add_f32_e32 v130, 1.0, v130
	v_add_f32_e32 v131, 1.0, v131
	v_add_f32_e32 v132, 1.0, v132
	v_add_f32_e32 v133, 1.0, v133
	v_add_f32_e32 v134, 1.0, v134
	v_add_f32_e32 v135, 1.0, v135
	v_add_f32_e32 v136, 1.0, v136
	v_add_f32_e32 v137, 1.0, v137
	v_rcp_f32_e32 v130, v130
	v_rcp_f32_e32 v131, v131
	v_rcp_f32_e32 v132, v132
	v_rcp_f32_e32 v133, v133
	v_rcp_f32_e32 v134, v134
	v_rcp_f32_e32 v136, v136
	v_rcp_f32_e32 v137, v137
	v_rcp_f32_e32 v135, v135
	v_pk_mul_f32 v[132:133], v[88:89], v[132:133]
	v_pk_mul_f32 v[130:131], v[86:87], v[130:131]
	v_pk_mul_f32 v[136:137], v[84:85], v[136:137]
	v_pk_mul_f32 v[134:135], v[82:83], v[134:135]
	s_mov_b64 s[12:13], 0

.LBB0_173:
	v_cvt_pk_bf16_f32 v130, v130, v131
	v_cvt_pk_bf16_f32 v131, v132, v133
	s_nop 0
	v_cvt_pk_bf16_f32 v132, v134, v135
	v_cvt_pk_bf16_f32 v133, v136, v137
	s_and_b64 vcc, exec, s[10:11]
	s_mov_b64 s[12:13], -1
	global_store_dwordx4 v[140:141], v[130:133], off offset:256 sc0 sc1
	s_cbranch_vccnz .LBB0_175
	s_nop 0
	v_mul_f32_e32 v130, 0xbfb8aa3b, v78
	v_mul_f32_e32 v131, 0xbfb8aa3b, v79
	v_mul_f32_e32 v132, 0xbfb8aa3b, v80
	v_mul_f32_e32 v133, 0xbfb8aa3b, v81
	v_mul_f32_e32 v134, 0xbfb8aa3b, v74
	v_mul_f32_e32 v135, 0xbfb8aa3b, v75
	v_mul_f32_e32 v136, 0xbfb8aa3b, v76
	v_mul_f32_e32 v137, 0xbfb8aa3b, v77
	v_exp_f32_e32 v130, v130
	v_exp_f32_e32 v131, v131
	v_exp_f32_e32 v132, v132
	v_exp_f32_e32 v133, v133
	v_exp_f32_e32 v134, v134
	v_exp_f32_e32 v135, v135
	v_exp_f32_e32 v136, v136
	v_exp_f32_e32 v137, v137
	v_add_f32_e32 v130, 1.0, v130
	v_add_f32_e32 v131, 1.0, v131
	v_add_f32_e32 v132, 1.0, v132
	v_add_f32_e32 v133, 1.0, v133
	v_add_f32_e32 v134, 1.0, v134
	v_add_f32_e32 v135, 1.0, v135
	v_add_f32_e32 v136, 1.0, v136
	v_add_f32_e32 v137, 1.0, v137
	v_rcp_f32_e32 v130, v130
	v_rcp_f32_e32 v131, v131
	v_rcp_f32_e32 v132, v132
	v_rcp_f32_e32 v133, v133
	v_rcp_f32_e32 v134, v134
	v_rcp_f32_e32 v136, v136
	v_rcp_f32_e32 v137, v137
	v_rcp_f32_e32 v135, v135
	v_pk_mul_f32 v[132:133], v[80:81], v[132:133]
	v_pk_mul_f32 v[130:131], v[78:79], v[130:131]
	v_pk_mul_f32 v[136:137], v[76:77], v[136:137]
	v_pk_mul_f32 v[134:135], v[74:75], v[134:135]
	s_mov_b64 s[12:13], 0

.LBB0_177:
	v_or_b32_e32 v140, 48, v208
	v_ashrrev_i32_e32 v141, 31, v140
	v_lshlrev_b64 v[140:141], 10, v[140:141]
	v_lshl_add_u64 v[140:141], v[138:139], 0, v[140:141]
	v_cvt_pk_bf16_f32 v130, v130, v131
	v_cvt_pk_bf16_f32 v131, v132, v133
	v_cvt_pk_bf16_f32 v132, v134, v135
	v_cvt_pk_bf16_f32 v133, v136, v137
	s_and_b64 vcc, exec, s[10:11]
	s_mov_b64 s[12:13], -1
	global_store_dwordx4 v[140:141], v[130:133], off sc0 sc1
	s_cbranch_vccnz .LBB0_179
	s_nop 0
	v_mul_f32_e32 v130, 0xbfb8aa3b, v70
	v_mul_f32_e32 v131, 0xbfb8aa3b, v71
	v_mul_f32_e32 v132, 0xbfb8aa3b, v72
	v_mul_f32_e32 v133, 0xbfb8aa3b, v73
	v_mul_f32_e32 v134, 0xbfb8aa3b, v66
	v_mul_f32_e32 v135, 0xbfb8aa3b, v67
	v_mul_f32_e32 v136, 0xbfb8aa3b, v68
	v_mul_f32_e32 v137, 0xbfb8aa3b, v69
	v_exp_f32_e32 v130, v130
	v_exp_f32_e32 v131, v131
	v_exp_f32_e32 v132, v132
	v_exp_f32_e32 v133, v133
	v_exp_f32_e32 v134, v134
	v_exp_f32_e32 v135, v135
	v_exp_f32_e32 v136, v136
	v_exp_f32_e32 v137, v137
	v_add_f32_e32 v130, 1.0, v130
	v_add_f32_e32 v131, 1.0, v131
	v_add_f32_e32 v132, 1.0, v132
	v_add_f32_e32 v133, 1.0, v133
	v_add_f32_e32 v134, 1.0, v134
	v_add_f32_e32 v135, 1.0, v135
	v_add_f32_e32 v136, 1.0, v136
	v_add_f32_e32 v137, 1.0, v137
	v_rcp_f32_e32 v130, v130
	v_rcp_f32_e32 v131, v131
	v_rcp_f32_e32 v132, v132
	v_rcp_f32_e32 v133, v133
	v_rcp_f32_e32 v134, v134
	v_rcp_f32_e32 v136, v136
	v_rcp_f32_e32 v137, v137
	v_rcp_f32_e32 v135, v135
	v_pk_mul_f32 v[132:133], v[72:73], v[132:133]
	v_pk_mul_f32 v[130:131], v[70:71], v[130:131]
	v_pk_mul_f32 v[136:137], v[68:69], v[136:137]
	v_pk_mul_f32 v[134:135], v[66:67], v[134:135]
	s_mov_b64 s[12:13], 0

.LBB0_181:
	v_cvt_pk_bf16_f32 v130, v130, v131
	v_cvt_pk_bf16_f32 v131, v132, v133
	s_nop 0
	v_cvt_pk_bf16_f32 v132, v134, v135
	v_cvt_pk_bf16_f32 v133, v136, v137
	s_and_b64 vcc, exec, s[10:11]
	s_mov_b64 s[12:13], -1
	global_store_dwordx4 v[140:141], v[130:133], off offset:256 sc0 sc1
	s_cbranch_vccnz .LBB0_183
	s_nop 0
	v_mul_f32_e32 v130, 0xbfb8aa3b, v62
	v_mul_f32_e32 v131, 0xbfb8aa3b, v63
	v_mul_f32_e32 v132, 0xbfb8aa3b, v64
	v_mul_f32_e32 v133, 0xbfb8aa3b, v65
	v_mul_f32_e32 v134, 0xbfb8aa3b, v58
	v_mul_f32_e32 v135, 0xbfb8aa3b, v59
	v_mul_f32_e32 v136, 0xbfb8aa3b, v60
	v_mul_f32_e32 v137, 0xbfb8aa3b, v61
	v_exp_f32_e32 v130, v130
	v_exp_f32_e32 v131, v131
	v_exp_f32_e32 v132, v132
	v_exp_f32_e32 v133, v133
	v_exp_f32_e32 v134, v134
	v_exp_f32_e32 v135, v135
	v_exp_f32_e32 v136, v136
	v_exp_f32_e32 v137, v137
	v_add_f32_e32 v130, 1.0, v130
	v_add_f32_e32 v131, 1.0, v131
	v_add_f32_e32 v132, 1.0, v132
	v_add_f32_e32 v133, 1.0, v133
	v_add_f32_e32 v134, 1.0, v134
	v_add_f32_e32 v135, 1.0, v135
	v_add_f32_e32 v136, 1.0, v136
	v_add_f32_e32 v137, 1.0, v137
	v_rcp_f32_e32 v130, v130
	v_rcp_f32_e32 v131, v131
	v_rcp_f32_e32 v132, v132
	v_rcp_f32_e32 v133, v133
	v_rcp_f32_e32 v134, v134
	v_rcp_f32_e32 v136, v136
	v_rcp_f32_e32 v137, v137
	v_rcp_f32_e32 v135, v135
	v_pk_mul_f32 v[132:133], v[64:65], v[132:133]
	v_pk_mul_f32 v[130:131], v[62:63], v[130:131]
	v_pk_mul_f32 v[136:137], v[60:61], v[136:137]
	v_pk_mul_f32 v[134:135], v[58:59], v[134:135]
	s_mov_b64 s[12:13], 0

.LBB0_185:
	v_lshlrev_b64 v[140:141], 10, v[208:209]
	v_lshl_add_u64 v[140:141], v[138:139], 0, v[140:141]
	v_cvt_pk_bf16_f32 v130, v130, v131
	v_cvt_pk_bf16_f32 v131, v132, v133
	v_cvt_pk_bf16_f32 v132, v134, v135
	v_add_co_u32_e32 v134, vcc, 0x20000, v140
	v_cvt_pk_bf16_f32 v133, v136, v137
	s_mov_b64 s[12:13], -1
	s_nop 0
	v_addc_co_u32_e32 v135, vcc, 0, v141, vcc
	s_and_b64 vcc, exec, s[10:11]
	global_store_dwordx4 v[134:135], v[130:133], off sc0 sc1
	s_cbranch_vccnz .LBB0_187
	s_nop 0
	v_mul_f32_e32 v130, 0xbfb8aa3b, v54
	v_mul_f32_e32 v131, 0xbfb8aa3b, v55
	v_mul_f32_e32 v132, 0xbfb8aa3b, v56
	v_mul_f32_e32 v133, 0xbfb8aa3b, v57
	v_mul_f32_e32 v134, 0xbfb8aa3b, v50
	v_mul_f32_e32 v135, 0xbfb8aa3b, v51
	v_mul_f32_e32 v136, 0xbfb8aa3b, v52
	v_mul_f32_e32 v137, 0xbfb8aa3b, v53
	v_exp_f32_e32 v130, v130
	v_exp_f32_e32 v131, v131
	v_exp_f32_e32 v132, v132
	v_exp_f32_e32 v133, v133
	v_exp_f32_e32 v134, v134
	v_exp_f32_e32 v135, v135
	v_exp_f32_e32 v136, v136
	v_exp_f32_e32 v137, v137
	v_add_f32_e32 v130, 1.0, v130
	v_add_f32_e32 v131, 1.0, v131
	v_add_f32_e32 v132, 1.0, v132
	v_add_f32_e32 v133, 1.0, v133
	v_add_f32_e32 v134, 1.0, v134
	v_add_f32_e32 v135, 1.0, v135
	v_add_f32_e32 v136, 1.0, v136
	v_add_f32_e32 v137, 1.0, v137
	v_rcp_f32_e32 v130, v130
	v_rcp_f32_e32 v131, v131
	v_rcp_f32_e32 v132, v132
	v_rcp_f32_e32 v133, v133
	v_rcp_f32_e32 v134, v134
	v_rcp_f32_e32 v136, v136
	v_rcp_f32_e32 v137, v137
	v_rcp_f32_e32 v135, v135
	v_pk_mul_f32 v[132:133], v[56:57], v[132:133]
	v_pk_mul_f32 v[130:131], v[54:55], v[130:131]
	v_pk_mul_f32 v[136:137], v[52:53], v[136:137]
	v_pk_mul_f32 v[134:135], v[50:51], v[134:135]
	s_mov_b64 s[12:13], 0

.LBB0_189:
	s_mov_b64 s[12:13], 0x20000
	v_lshl_add_u64 v[140:141], v[140:141], 0, s[12:13]
	v_cvt_pk_bf16_f32 v130, v130, v131
	v_cvt_pk_bf16_f32 v131, v132, v133
	v_cvt_pk_bf16_f32 v132, v134, v135
	v_cvt_pk_bf16_f32 v133, v136, v137
	s_and_b64 vcc, exec, s[10:11]
	s_mov_b64 s[12:13], -1
	global_store_dwordx4 v[140:141], v[130:133], off offset:256 sc0 sc1
	s_cbranch_vccnz .LBB0_191
	s_nop 0
	v_mul_f32_e32 v130, 0xbfb8aa3b, v46
	v_mul_f32_e32 v131, 0xbfb8aa3b, v47
	v_mul_f32_e32 v132, 0xbfb8aa3b, v48
	v_mul_f32_e32 v133, 0xbfb8aa3b, v49
	v_mul_f32_e32 v134, 0xbfb8aa3b, v42
	v_mul_f32_e32 v135, 0xbfb8aa3b, v43
	v_mul_f32_e32 v136, 0xbfb8aa3b, v44
	v_mul_f32_e32 v137, 0xbfb8aa3b, v45
	v_exp_f32_e32 v130, v130
	v_exp_f32_e32 v131, v131
	v_exp_f32_e32 v132, v132
	v_exp_f32_e32 v133, v133
	v_exp_f32_e32 v134, v134
	v_exp_f32_e32 v135, v135
	v_exp_f32_e32 v136, v136
	v_exp_f32_e32 v137, v137
	v_add_f32_e32 v130, 1.0, v130
	v_add_f32_e32 v131, 1.0, v131
	v_add_f32_e32 v132, 1.0, v132
	v_add_f32_e32 v133, 1.0, v133
	v_add_f32_e32 v134, 1.0, v134
	v_add_f32_e32 v135, 1.0, v135
	v_add_f32_e32 v136, 1.0, v136
	v_add_f32_e32 v137, 1.0, v137
	v_rcp_f32_e32 v130, v130
	v_rcp_f32_e32 v131, v131
	v_rcp_f32_e32 v132, v132
	v_rcp_f32_e32 v133, v133
	v_rcp_f32_e32 v134, v134
	v_rcp_f32_e32 v136, v136
	v_rcp_f32_e32 v137, v137
	v_rcp_f32_e32 v135, v135
	v_pk_mul_f32 v[132:133], v[48:49], v[132:133]
	v_pk_mul_f32 v[130:131], v[46:47], v[130:131]
	v_pk_mul_f32 v[136:137], v[44:45], v[136:137]
	v_pk_mul_f32 v[134:135], v[42:43], v[134:135]
	s_mov_b64 s[12:13], 0

.LBB0_193:
	v_lshlrev_b64 v[140:141], 10, v[208:209]
	v_lshl_add_u64 v[140:141], v[138:139], 0, v[140:141]
	v_cvt_pk_bf16_f32 v130, v130, v131
	v_cvt_pk_bf16_f32 v131, v132, v133
	v_cvt_pk_bf16_f32 v132, v134, v135
	v_add_co_u32_e32 v134, vcc, 0x24000, v140
	v_cvt_pk_bf16_f32 v133, v136, v137
	s_mov_b64 s[12:13], -1
	s_nop 0
	v_addc_co_u32_e32 v135, vcc, 0, v141, vcc
	s_and_b64 vcc, exec, s[10:11]
	global_store_dwordx4 v[134:135], v[130:133], off sc0 sc1
	s_cbranch_vccnz .LBB0_195
	s_nop 0
	v_mul_f32_e32 v130, 0xbfb8aa3b, v38
	v_mul_f32_e32 v131, 0xbfb8aa3b, v39
	v_mul_f32_e32 v132, 0xbfb8aa3b, v40
	v_mul_f32_e32 v133, 0xbfb8aa3b, v41
	v_mul_f32_e32 v134, 0xbfb8aa3b, v34
	v_mul_f32_e32 v135, 0xbfb8aa3b, v35
	v_mul_f32_e32 v136, 0xbfb8aa3b, v36
	v_mul_f32_e32 v137, 0xbfb8aa3b, v37
	v_exp_f32_e32 v130, v130
	v_exp_f32_e32 v131, v131
	v_exp_f32_e32 v132, v132
	v_exp_f32_e32 v133, v133
	v_exp_f32_e32 v134, v134
	v_exp_f32_e32 v135, v135
	v_exp_f32_e32 v136, v136
	v_exp_f32_e32 v137, v137
	v_add_f32_e32 v130, 1.0, v130
	v_add_f32_e32 v131, 1.0, v131
	v_add_f32_e32 v132, 1.0, v132
	v_add_f32_e32 v133, 1.0, v133
	v_add_f32_e32 v134, 1.0, v134
	v_add_f32_e32 v135, 1.0, v135
	v_add_f32_e32 v136, 1.0, v136
	v_add_f32_e32 v137, 1.0, v137
	v_rcp_f32_e32 v130, v130
	v_rcp_f32_e32 v131, v131
	v_rcp_f32_e32 v132, v132
	v_rcp_f32_e32 v133, v133
	v_rcp_f32_e32 v134, v134
	v_rcp_f32_e32 v136, v136
	v_rcp_f32_e32 v137, v137
	v_rcp_f32_e32 v135, v135
	v_pk_mul_f32 v[132:133], v[40:41], v[132:133]
	v_pk_mul_f32 v[130:131], v[38:39], v[130:131]
	v_pk_mul_f32 v[136:137], v[36:37], v[136:137]
	v_pk_mul_f32 v[134:135], v[34:35], v[134:135]
	s_mov_b64 s[12:13], 0

.LBB0_197:
	s_mov_b64 s[12:13], 0x24000
	v_lshl_add_u64 v[140:141], v[140:141], 0, s[12:13]
	v_cvt_pk_bf16_f32 v130, v130, v131
	v_cvt_pk_bf16_f32 v131, v132, v133
	v_cvt_pk_bf16_f32 v132, v134, v135
	v_cvt_pk_bf16_f32 v133, v136, v137
	s_and_b64 vcc, exec, s[10:11]
	s_mov_b64 s[12:13], -1
	global_store_dwordx4 v[140:141], v[130:133], off offset:256 sc0 sc1
	s_cbranch_vccnz .LBB0_199
	s_nop 0
	v_mul_f32_e32 v130, 0xbfb8aa3b, v30
	v_mul_f32_e32 v131, 0xbfb8aa3b, v31
	v_mul_f32_e32 v132, 0xbfb8aa3b, v32
	v_mul_f32_e32 v133, 0xbfb8aa3b, v33
	v_mul_f32_e32 v134, 0xbfb8aa3b, v26
	v_mul_f32_e32 v135, 0xbfb8aa3b, v27
	v_mul_f32_e32 v136, 0xbfb8aa3b, v28
	v_mul_f32_e32 v137, 0xbfb8aa3b, v29
	v_exp_f32_e32 v130, v130
	v_exp_f32_e32 v131, v131
	v_exp_f32_e32 v132, v132
	v_exp_f32_e32 v133, v133
	v_exp_f32_e32 v134, v134
	v_exp_f32_e32 v135, v135
	v_exp_f32_e32 v136, v136
	v_exp_f32_e32 v137, v137
	v_add_f32_e32 v130, 1.0, v130
	v_add_f32_e32 v131, 1.0, v131
	v_add_f32_e32 v132, 1.0, v132
	v_add_f32_e32 v133, 1.0, v133
	v_add_f32_e32 v134, 1.0, v134
	v_add_f32_e32 v135, 1.0, v135
	v_add_f32_e32 v136, 1.0, v136
	v_add_f32_e32 v137, 1.0, v137
	v_rcp_f32_e32 v130, v130
	v_rcp_f32_e32 v131, v131
	v_rcp_f32_e32 v132, v132
	v_rcp_f32_e32 v133, v133
	v_rcp_f32_e32 v134, v134
	v_rcp_f32_e32 v136, v136
	v_rcp_f32_e32 v137, v137
	v_rcp_f32_e32 v135, v135
	v_pk_mul_f32 v[132:133], v[32:33], v[132:133]
	v_pk_mul_f32 v[130:131], v[30:31], v[130:131]
	v_pk_mul_f32 v[136:137], v[28:29], v[136:137]
	v_pk_mul_f32 v[134:135], v[26:27], v[134:135]
	s_mov_b64 s[12:13], 0

.LBB0_201:
	v_lshlrev_b64 v[140:141], 10, v[208:209]
	v_lshl_add_u64 v[140:141], v[138:139], 0, v[140:141]
	v_cvt_pk_bf16_f32 v130, v130, v131
	v_cvt_pk_bf16_f32 v131, v132, v133
	v_cvt_pk_bf16_f32 v132, v134, v135
	v_add_co_u32_e32 v134, vcc, 0x28000, v140
	v_cvt_pk_bf16_f32 v133, v136, v137
	s_mov_b64 s[12:13], -1
	s_nop 0
	v_addc_co_u32_e32 v135, vcc, 0, v141, vcc
	s_and_b64 vcc, exec, s[10:11]
	global_store_dwordx4 v[134:135], v[130:133], off sc0 sc1
	s_cbranch_vccnz .LBB0_203
	s_nop 0
	v_mul_f32_e32 v130, 0xbfb8aa3b, v22
	v_mul_f32_e32 v131, 0xbfb8aa3b, v23
	v_mul_f32_e32 v132, 0xbfb8aa3b, v24
	v_mul_f32_e32 v133, 0xbfb8aa3b, v25
	v_mul_f32_e32 v134, 0xbfb8aa3b, v18
	v_mul_f32_e32 v135, 0xbfb8aa3b, v19
	v_mul_f32_e32 v136, 0xbfb8aa3b, v20
	v_mul_f32_e32 v137, 0xbfb8aa3b, v21
	v_exp_f32_e32 v130, v130
	v_exp_f32_e32 v131, v131
	v_exp_f32_e32 v132, v132
	v_exp_f32_e32 v133, v133
	v_exp_f32_e32 v134, v134
	v_exp_f32_e32 v135, v135
	v_exp_f32_e32 v136, v136
	v_exp_f32_e32 v137, v137
	v_add_f32_e32 v130, 1.0, v130
	v_add_f32_e32 v131, 1.0, v131
	v_add_f32_e32 v132, 1.0, v132
	v_add_f32_e32 v133, 1.0, v133
	v_add_f32_e32 v134, 1.0, v134
	v_add_f32_e32 v135, 1.0, v135
	v_add_f32_e32 v136, 1.0, v136
	v_add_f32_e32 v137, 1.0, v137
	v_rcp_f32_e32 v130, v130
	v_rcp_f32_e32 v131, v131
	v_rcp_f32_e32 v132, v132
	v_rcp_f32_e32 v133, v133
	v_rcp_f32_e32 v134, v134
	v_rcp_f32_e32 v136, v136
	v_rcp_f32_e32 v137, v137
	v_rcp_f32_e32 v135, v135
	v_pk_mul_f32 v[132:133], v[24:25], v[132:133]
	v_pk_mul_f32 v[130:131], v[22:23], v[130:131]
	v_pk_mul_f32 v[136:137], v[20:21], v[136:137]
	v_pk_mul_f32 v[134:135], v[18:19], v[134:135]
	s_mov_b64 s[12:13], 0

.LBB0_205:
	s_mov_b64 s[12:13], 0x28000
	v_lshl_add_u64 v[140:141], v[140:141], 0, s[12:13]
	v_cvt_pk_bf16_f32 v130, v130, v131
	v_cvt_pk_bf16_f32 v131, v132, v133
	v_cvt_pk_bf16_f32 v132, v134, v135
	v_cvt_pk_bf16_f32 v133, v136, v137
	s_and_b64 vcc, exec, s[10:11]
	s_mov_b64 s[12:13], -1
	global_store_dwordx4 v[140:141], v[130:133], off offset:256 sc0 sc1
	s_cbranch_vccnz .LBB0_207
	s_nop 0
	v_mul_f32_e32 v130, 0xbfb8aa3b, v14
	v_mul_f32_e32 v131, 0xbfb8aa3b, v15
	v_mul_f32_e32 v132, 0xbfb8aa3b, v16
	v_mul_f32_e32 v133, 0xbfb8aa3b, v17
	v_mul_f32_e32 v134, 0xbfb8aa3b, v10
	v_mul_f32_e32 v135, 0xbfb8aa3b, v11
	v_mul_f32_e32 v136, 0xbfb8aa3b, v12
	v_mul_f32_e32 v137, 0xbfb8aa3b, v13
	v_exp_f32_e32 v130, v130
	v_exp_f32_e32 v131, v131
	v_exp_f32_e32 v132, v132
	v_exp_f32_e32 v133, v133
	v_exp_f32_e32 v134, v134
	v_exp_f32_e32 v135, v135
	v_exp_f32_e32 v136, v136
	v_exp_f32_e32 v137, v137
	v_add_f32_e32 v130, 1.0, v130
	v_add_f32_e32 v131, 1.0, v131
	v_add_f32_e32 v132, 1.0, v132
	v_add_f32_e32 v133, 1.0, v133
	v_add_f32_e32 v134, 1.0, v134
	v_add_f32_e32 v135, 1.0, v135
	v_add_f32_e32 v136, 1.0, v136
	v_add_f32_e32 v137, 1.0, v137
	v_rcp_f32_e32 v130, v130
	v_rcp_f32_e32 v131, v131
	v_rcp_f32_e32 v132, v132
	v_rcp_f32_e32 v133, v133
	v_rcp_f32_e32 v134, v134
	v_rcp_f32_e32 v136, v136
	v_rcp_f32_e32 v137, v137
	v_rcp_f32_e32 v135, v135
	v_pk_mul_f32 v[132:133], v[16:17], v[132:133]
	v_pk_mul_f32 v[130:131], v[14:15], v[130:131]
	v_pk_mul_f32 v[136:137], v[12:13], v[136:137]
	v_pk_mul_f32 v[134:135], v[10:11], v[134:135]
	s_mov_b64 s[12:13], 0

.LBB0_209:
	v_lshlrev_b64 v[140:141], 10, v[208:209]
	v_lshl_add_u64 v[138:139], v[138:139], 0, v[140:141]
	v_cvt_pk_bf16_f32 v130, v130, v131
	v_cvt_pk_bf16_f32 v131, v132, v133
	v_cvt_pk_bf16_f32 v132, v134, v135
	v_add_co_u32_e32 v134, vcc, 0x2c000, v138
	v_cvt_pk_bf16_f32 v133, v136, v137
	s_nop 1
	v_addc_co_u32_e32 v135, vcc, 0, v139, vcc
	s_and_b64 vcc, exec, s[10:11]
	s_mov_b64 s[10:11], -1
	global_store_dwordx4 v[134:135], v[130:133], off sc0 sc1
	s_cbranch_vccnz .LBB0_211
	s_nop 0
	v_mul_f32_e32 v130, 0xbfb8aa3b, v6
	v_mul_f32_e32 v131, 0xbfb8aa3b, v7
	v_mul_f32_e32 v132, 0xbfb8aa3b, v8
	v_mul_f32_e32 v133, 0xbfb8aa3b, v9
	v_mul_f32_e32 v134, 0xbfb8aa3b, v2
	v_mul_f32_e32 v135, 0xbfb8aa3b, v3
	v_mul_f32_e32 v136, 0xbfb8aa3b, v4
	v_mul_f32_e32 v137, 0xbfb8aa3b, v5
	v_exp_f32_e32 v130, v130
	v_exp_f32_e32 v131, v131
	v_exp_f32_e32 v132, v132
	v_exp_f32_e32 v133, v133
	v_exp_f32_e32 v134, v134
	v_exp_f32_e32 v135, v135
	v_exp_f32_e32 v136, v136
	v_exp_f32_e32 v137, v137
	v_add_f32_e32 v130, 1.0, v130
	v_add_f32_e32 v131, 1.0, v131
	v_add_f32_e32 v132, 1.0, v132
	v_add_f32_e32 v133, 1.0, v133
	v_add_f32_e32 v134, 1.0, v134
	v_add_f32_e32 v135, 1.0, v135
	v_add_f32_e32 v136, 1.0, v136
	v_add_f32_e32 v137, 1.0, v137
	v_rcp_f32_e32 v130, v130
	v_rcp_f32_e32 v131, v131
	v_rcp_f32_e32 v132, v132
	v_rcp_f32_e32 v133, v133
	v_rcp_f32_e32 v134, v134
	v_rcp_f32_e32 v136, v136
	v_rcp_f32_e32 v137, v137
	v_rcp_f32_e32 v135, v135
	v_pk_mul_f32 v[132:133], v[8:9], v[132:133]
	v_pk_mul_f32 v[130:131], v[6:7], v[130:131]
	v_pk_mul_f32 v[136:137], v[4:5], v[136:137]
	v_pk_mul_f32 v[134:135], v[2:3], v[134:135]
	s_mov_b64 s[10:11], 0

.LBB0_213:
	s_mov_b64 s[10:11], 0x2c000
	v_lshl_add_u64 v[138:139], v[138:139], 0, s[10:11]
	v_cvt_pk_bf16_f32 v130, v130, v131
	v_cvt_pk_bf16_f32 v131, v132, v133
	v_cvt_pk_bf16_f32 v132, v134, v135
	v_cvt_pk_bf16_f32 v133, v136, v137
	global_store_dwordx4 v[138:139], v[130:133], off offset:256 sc0 sc1
	s_mov_b64 s[10:11], 0

.LBB0_219:
	s_and_b64 vcc, s[10:11], exec
	s_cselect_b32 s54, 9, 4
	s_add_u32 s62, s30, s62
	v_lshlrev_b32_e32 v131, s54, v185
	s_addc_u32 s63, s31, s63
	v_or_b32_e32 v174, s42, v131
	v_ashrrev_i32_e32 v133, 31, v132
	s_and_b64 s[10:11], s[10:11], exec
	v_lshl_add_u64 v[136:137], s[62:63], 0, v[174:175]
	v_lshlrev_b64 v[132:133], 12, v[132:133]
	s_cselect_b32 s57, 4, 6
	v_lshl_add_u64 v[136:137], v[136:137], 0, v[132:133]
	v_lshlrev_b32_e32 v132, s57, v1
	v_mov_b32_e32 v133, v175
	v_lshl_add_u64 v[136:137], v[136:137], 0, v[132:133]
	v_cmp_ne_u64_e32 vcc, 0, v[134:135]
	v_cvt_pk_bf16_f32 v138, v126, v127
	v_cvt_pk_bf16_f32 v139, v128, v129
	v_cvt_pk_bf16_f32 v140, v122, v123
	v_cvt_pk_bf16_f32 v141, v124, v125
	global_store_dwordx4 v[136:137], v[138:141], off sc0 sc1
	s_and_saveexec_b64 s[10:11], vcc
	s_cbranch_execz .LBB0_221
	global_store_dwordx4 v[134:135], v[126:129], off nt
	global_store_dwordx4 v[134:135], v[122:125], off offset:16 nt
.LBB0_221:
	s_or_b64 exec, exec, s[10:11]
	v_lshl_add_u64 v[140:141], v[136:137], 0, s[60:61]
	v_cvt_pk_bf16_f32 v136, v118, v119
	v_cvt_pk_bf16_f32 v137, v120, v121
	v_cvt_pk_bf16_f32 v138, v114, v115
	v_cvt_pk_bf16_f32 v139, v116, v117
	global_store_dwordx4 v[140:141], v[136:139], off sc0 sc1
	s_and_saveexec_b64 s[10:11], vcc
	s_cbranch_execz .LBB0_223
	global_store_dwordx4 v[134:135], v[118:121], off offset:512 nt
	global_store_dwordx4 v[134:135], v[114:117], off offset:528 nt

.LBB0_227:
	s_add_u32 s62, s30, s62
	s_addc_u32 s63, s31, s63
	v_ashrrev_i32_e32 v135, 31, v134
	v_lshl_add_u64 v[138:139], s[62:63], 0, v[174:175]
	v_lshlrev_b64 v[134:135], 12, v[134:135]
	v_lshl_add_u64 v[138:139], v[138:139], 0, v[134:135]
	v_lshlrev_b32_e32 v134, s57, v197
	v_mov_b32_e32 v135, v175
	v_lshl_add_u64 v[138:139], v[138:139], 0, v[134:135]
	v_cmp_ne_u64_e32 vcc, 0, v[136:137]
	v_cvt_pk_bf16_f32 v140, v110, v111
	v_cvt_pk_bf16_f32 v141, v112, v113
	v_cvt_pk_bf16_f32 v142, v106, v107
	v_cvt_pk_bf16_f32 v143, v108, v109
	global_store_dwordx4 v[138:139], v[140:143], off sc0 sc1
	s_and_saveexec_b64 s[62:63], vcc
	s_cbranch_execz .LBB0_229
	global_store_dwordx4 v[136:137], v[110:113], off nt
	global_store_dwordx4 v[136:137], v[106:109], off offset:16 nt
.LBB0_229:
	s_or_b64 exec, exec, s[62:63]
	v_lshl_add_u64 v[142:143], v[138:139], 0, s[60:61]
	v_cvt_pk_bf16_f32 v138, v102, v103
	v_cvt_pk_bf16_f32 v139, v104, v105
	v_cvt_pk_bf16_f32 v140, v98, v99
	v_cvt_pk_bf16_f32 v141, v100, v101
	global_store_dwordx4 v[142:143], v[138:141], off sc0 sc1
	s_and_saveexec_b64 s[60:61], vcc
	s_cbranch_execz .LBB0_231
	global_store_dwordx4 v[136:137], v[102:105], off offset:512 nt
	global_store_dwordx4 v[136:137], v[98:101], off offset:528 nt

.LBB0_236:
	s_add_u32 s54, s30, s62
	s_addc_u32 s55, s31, s63
	v_ashrrev_i32_e32 v139, 31, v138
	v_lshl_add_u64 v[140:141], s[54:55], 0, v[174:175]
	v_lshlrev_b64 v[138:139], 12, v[138:139]
	v_lshl_add_u64 v[138:139], v[140:141], 0, v[138:139]
	v_lshl_add_u64 v[138:139], v[138:139], 0, v[132:133]
	v_cmp_ne_u64_e32 vcc, 0, v[136:137]
	v_cvt_pk_bf16_f32 v140, v94, v95
	v_cvt_pk_bf16_f32 v141, v96, v97
	v_cvt_pk_bf16_f32 v142, v90, v91
	v_cvt_pk_bf16_f32 v143, v92, v93
	global_store_dwordx4 v[138:139], v[140:143], off sc0 sc1
	s_and_saveexec_b64 s[62:63], vcc
	s_cbranch_execz .LBB0_238
	global_store_dwordx4 v[136:137], v[94:97], off nt
	global_store_dwordx4 v[136:137], v[90:93], off offset:16 nt
.LBB0_238:
	s_or_b64 exec, exec, s[62:63]
	v_lshl_add_u64 v[142:143], v[138:139], 0, s[60:61]
	v_cvt_pk_bf16_f32 v138, v86, v87
	v_cvt_pk_bf16_f32 v139, v88, v89
	v_cvt_pk_bf16_f32 v140, v82, v83
	v_cvt_pk_bf16_f32 v141, v84, v85
	global_store_dwordx4 v[142:143], v[138:141], off sc0 sc1
	s_and_saveexec_b64 s[60:61], vcc
	s_cbranch_execz .LBB0_240
	global_store_dwordx4 v[136:137], v[86:89], off offset:512 nt
	global_store_dwordx4 v[136:137], v[82:85], off offset:528 nt

.LBB0_244:
	s_add_u32 s54, s30, s62
	s_addc_u32 s55, s31, s63
	v_ashrrev_i32_e32 v139, 31, v138
	v_lshl_add_u64 v[140:141], s[54:55], 0, v[174:175]
	v_lshlrev_b64 v[138:139], 12, v[138:139]
	v_lshl_add_u64 v[138:139], v[140:141], 0, v[138:139]
	v_lshl_add_u64 v[138:139], v[138:139], 0, v[134:135]
	v_cmp_ne_u64_e32 vcc, 0, v[136:137]
	v_cvt_pk_bf16_f32 v140, v78, v79
	v_cvt_pk_bf16_f32 v141, v80, v81
	v_cvt_pk_bf16_f32 v142, v74, v75
	v_cvt_pk_bf16_f32 v143, v76, v77
	global_store_dwordx4 v[138:139], v[140:143], off sc0 sc1
	s_and_saveexec_b64 s[62:63], vcc
	s_cbranch_execz .LBB0_246
	global_store_dwordx4 v[136:137], v[78:81], off nt
	global_store_dwordx4 v[136:137], v[74:77], off offset:16 nt
.LBB0_246:
	s_or_b64 exec, exec, s[62:63]
	v_lshl_add_u64 v[142:143], v[138:139], 0, s[60:61]
	v_cvt_pk_bf16_f32 v138, v70, v71
	v_cvt_pk_bf16_f32 v139, v72, v73
	v_cvt_pk_bf16_f32 v140, v66, v67
	v_cvt_pk_bf16_f32 v141, v68, v69
	global_store_dwordx4 v[142:143], v[138:141], off sc0 sc1
	s_and_saveexec_b64 s[60:61], vcc
	s_cbranch_execz .LBB0_248
	global_store_dwordx4 v[136:137], v[70:73], off offset:512 nt
	global_store_dwordx4 v[136:137], v[66:69], off offset:528 nt

.LBB0_252:
	s_add_u32 s54, s30, s62
	s_addc_u32 s55, s31, s63
	v_ashrrev_i32_e32 v139, 31, v138
	v_lshl_add_u64 v[142:143], s[54:55], 0, v[174:175]
	v_lshlrev_b64 v[138:139], 12, v[138:139]
	v_lshl_add_u64 v[138:139], v[142:143], 0, v[138:139]
	v_lshl_add_u64 v[138:139], v[138:139], 0, v[132:133]
	v_cmp_ne_u64_e32 vcc, 0, v[136:137]
	v_cvt_pk_bf16_f32 v142, v62, v63
	v_cvt_pk_bf16_f32 v143, v64, v65
	v_cvt_pk_bf16_f32 v144, v58, v59
	v_cvt_pk_bf16_f32 v145, v60, v61
	global_store_dwordx4 v[138:139], v[142:145], off sc0 sc1
	s_and_saveexec_b64 s[62:63], vcc
	s_cbranch_execz .LBB0_254
	global_store_dwordx4 v[136:137], v[62:65], off nt
	global_store_dwordx4 v[136:137], v[58:61], off offset:16 nt
.LBB0_254:
	s_or_b64 exec, exec, s[62:63]
	v_lshl_add_u64 v[138:139], v[138:139], 0, s[60:61]
	v_cvt_pk_bf16_f32 v142, v54, v55
	v_cvt_pk_bf16_f32 v143, v56, v57
	v_cvt_pk_bf16_f32 v144, v50, v51
	v_cvt_pk_bf16_f32 v145, v52, v53
	global_store_dwordx4 v[138:139], v[142:145], off sc0 sc1
	s_and_saveexec_b64 s[60:61], vcc
	s_cbranch_execz .LBB0_256
	global_store_dwordx4 v[136:137], v[54:57], off offset:512 nt
	global_store_dwordx4 v[136:137], v[50:53], off offset:528 nt

.LBB0_260:
	s_add_u32 s54, s30, s62
	s_addc_u32 s55, s31, s63
	v_ashrrev_i32_e32 v139, 31, v138
	v_lshl_add_u64 v[142:143], s[54:55], 0, v[174:175]
	v_lshlrev_b64 v[138:139], 12, v[138:139]
	v_lshl_add_u64 v[138:139], v[142:143], 0, v[138:139]
	v_lshl_add_u64 v[138:139], v[138:139], 0, v[134:135]
	v_cmp_ne_u64_e32 vcc, 0, v[136:137]
	v_cvt_pk_bf16_f32 v142, v46, v47
	v_cvt_pk_bf16_f32 v143, v48, v49
	v_cvt_pk_bf16_f32 v144, v42, v43
	v_cvt_pk_bf16_f32 v145, v44, v45
	global_store_dwordx4 v[138:139], v[142:145], off sc0 sc1
	s_and_saveexec_b64 s[62:63], vcc
	s_cbranch_execz .LBB0_262
	global_store_dwordx4 v[136:137], v[46:49], off nt
	global_store_dwordx4 v[136:137], v[42:45], off offset:16 nt
.LBB0_262:
	s_or_b64 exec, exec, s[62:63]
	v_lshl_add_u64 v[138:139], v[138:139], 0, s[60:61]
	v_cvt_pk_bf16_f32 v142, v38, v39
	v_cvt_pk_bf16_f32 v143, v40, v41
	v_cvt_pk_bf16_f32 v144, v34, v35
	v_cvt_pk_bf16_f32 v145, v36, v37
	global_store_dwordx4 v[138:139], v[142:145], off sc0 sc1
	s_and_saveexec_b64 s[60:61], vcc
	s_cbranch_execz .LBB0_264
	global_store_dwordx4 v[136:137], v[38:41], off offset:512 nt
	global_store_dwordx4 v[136:137], v[34:37], off offset:528 nt

.LBB0_268:
	s_add_u32 s54, s30, s62
	s_addc_u32 s55, s31, s63
	v_ashrrev_i32_e32 v139, 31, v138
	v_lshl_add_u64 v[142:143], s[54:55], 0, v[174:175]
	v_lshlrev_b64 v[138:139], 12, v[138:139]
	v_lshl_add_u64 v[138:139], v[142:143], 0, v[138:139]
	v_lshl_add_u64 v[132:133], v[138:139], 0, v[132:133]
	v_cmp_ne_u64_e32 vcc, 0, v[136:137]
	v_cvt_pk_bf16_f32 v142, v30, v31
	v_cvt_pk_bf16_f32 v143, v32, v33
	v_cvt_pk_bf16_f32 v144, v26, v27
	v_cvt_pk_bf16_f32 v145, v28, v29
	global_store_dwordx4 v[132:133], v[142:145], off sc0 sc1
	s_and_saveexec_b64 s[62:63], vcc
	s_cbranch_execz .LBB0_270
	global_store_dwordx4 v[136:137], v[30:33], off nt
	global_store_dwordx4 v[136:137], v[26:29], off offset:16 nt
.LBB0_270:
	s_or_b64 exec, exec, s[62:63]
	v_lshl_add_u64 v[132:133], v[132:133], 0, s[60:61]
	v_cvt_pk_bf16_f32 v142, v22, v23
	v_cvt_pk_bf16_f32 v143, v24, v25
	v_cvt_pk_bf16_f32 v144, v18, v19
	v_cvt_pk_bf16_f32 v145, v20, v21
	global_store_dwordx4 v[132:133], v[142:145], off sc0 sc1
	s_and_saveexec_b64 s[60:61], vcc
	s_cbranch_execz .LBB0_272
	global_store_dwordx4 v[136:137], v[22:25], off offset:512 nt
	global_store_dwordx4 v[136:137], v[18:21], off offset:528 nt

.LBB0_276:
	s_add_u32 s12, s30, s60
	s_addc_u32 s13, s31, s61
	v_ashrrev_i32_e32 v137, 31, v136
	v_lshl_add_u64 v[130:131], s[12:13], 0, v[174:175]
	v_lshlrev_b64 v[136:137], 12, v[136:137]
	v_lshl_add_u64 v[130:131], v[130:131], 0, v[136:137]
	v_lshl_add_u64 v[130:131], v[130:131], 0, v[134:135]
	v_cmp_ne_u64_e32 vcc, 0, v[132:133]
	v_cvt_pk_bf16_f32 v134, v14, v15
	v_cvt_pk_bf16_f32 v135, v16, v17
	v_cvt_pk_bf16_f32 v136, v10, v11
	v_cvt_pk_bf16_f32 v137, v12, v13
	global_store_dwordx4 v[130:131], v[134:137], off sc0 sc1
	s_and_saveexec_b64 s[12:13], vcc
	s_cbranch_execz .LBB0_278
	global_store_dwordx4 v[132:133], v[14:17], off nt
	global_store_dwordx4 v[132:133], v[10:13], off offset:16 nt
.LBB0_278:
	s_or_b64 exec, exec, s[12:13]
	v_lshl_add_u64 v[130:131], v[130:131], 0, s[10:11]
	v_cvt_pk_bf16_f32 v134, v6, v7
	v_cvt_pk_bf16_f32 v135, v8, v9
	v_cvt_pk_bf16_f32 v136, v2, v3
	v_cvt_pk_bf16_f32 v137, v4, v5
	global_store_dwordx4 v[130:131], v[134:137], off sc0 sc1
	s_and_saveexec_b64 s[10:11], vcc
	s_cbranch_execz .LBB0_280
	global_store_dwordx4 v[132:133], v[6:9], off offset:512 nt
	global_store_dwordx4 v[132:133], v[2:5], off offset:528 nt

.LBB0_294:
	s_andn2_b64 vcc, exec, s[60:61]
	s_cbranch_vccnz .LBB0_298
	s_add_u32 s56, s30, s94
	s_addc_u32 s57, s31, 0
	v_lshl_add_u64 v[122:123], s[56:57], 0, v[214:215]
	v_lshl_add_u64 v[122:123], v[122:123], 0, s[42:43]
	v_lshl_add_u64 v[122:123], v[122:123], 0, v[180:181]
	v_lshl_add_u64 v[128:129], v[122:123], 0, v[176:177]
	v_cvt_pk_bf16_f32 v122, v118, v119
	v_cvt_pk_bf16_f32 v123, v120, v121
	v_cvt_pk_bf16_f32 v124, v114, v115
	v_cvt_pk_bf16_f32 v125, v116, v117
	global_store_dwordx4 v[128:129], v[122:125], off sc0 sc1
	s_and_saveexec_b64 s[60:61], s[12:13]
	s_cbranch_execz .LBB0_297
	s_lshl_b32 s26, s63, 2
	v_lshl_add_u64 v[122:123], v[210:211], 0, s[26:27]
	v_lshlrev_b32_e32 v174, 2, v192
	v_lshl_add_u64 v[122:123], v[122:123], 0, v[174:175]
	global_store_dwordx4 v[122:123], v[118:121], off nt
	global_store_dwordx4 v[122:123], v[114:117], off offset:16 nt

.LBB0_313:
	s_add_u32 s56, s30, s94
	s_addc_u32 s57, s31, 0
	v_lshl_add_u64 v[106:107], s[56:57], 0, v[110:111]
	v_lshl_add_u64 v[106:107], v[106:107], 0, s[42:43]
	v_lshl_add_u64 v[106:107], v[106:107], 0, v[186:187]
	v_lshl_add_u64 v[110:111], v[106:107], 0, v[176:177]
	v_cvt_pk_bf16_f32 v106, v102, v103
	v_cvt_pk_bf16_f32 v107, v104, v105
	v_cvt_pk_bf16_f32 v108, v98, v99
	v_cvt_pk_bf16_f32 v109, v100, v101
	global_store_dwordx4 v[110:111], v[106:109], off sc0 sc1
	s_and_saveexec_b64 s[60:61], s[14:15]
	s_cbranch_execz .LBB0_315
	s_lshl_b32 s26, s63, 2
	v_lshl_add_u64 v[106:107], v[118:119], 0, s[26:27]
	v_lshlrev_b32_e32 v174, 2, v192
	v_lshl_add_u64 v[106:107], v[106:107], 0, v[174:175]
	global_store_dwordx4 v[106:107], v[102:105], off nt
	global_store_dwordx4 v[106:107], v[98:101], off offset:16 nt

.LBB0_329:
	s_add_u32 s56, s30, s94
	s_addc_u32 s57, s31, 0
	v_lshl_add_u64 v[90:91], s[56:57], 0, v[94:95]
	v_lshl_add_u64 v[90:91], v[90:91], 0, s[42:43]
	v_lshl_add_u64 v[90:91], v[90:91], 0, v[180:181]
	v_lshl_add_u64 v[94:95], v[90:91], 0, v[176:177]
	v_cvt_pk_bf16_f32 v90, v86, v87
	v_cvt_pk_bf16_f32 v91, v88, v89
	v_cvt_pk_bf16_f32 v92, v82, v83
	v_cvt_pk_bf16_f32 v93, v84, v85
	global_store_dwordx4 v[94:95], v[90:93], off sc0 sc1
	s_and_saveexec_b64 s[60:61], s[14:15]
	s_cbranch_execz .LBB0_331
	s_lshl_b32 s26, s63, 2
	v_lshl_add_u64 v[90:91], v[102:103], 0, s[26:27]
	v_lshlrev_b32_e32 v174, 2, v192
	v_lshl_add_u64 v[90:91], v[90:91], 0, v[174:175]
	global_store_dwordx4 v[90:91], v[86:89], off nt
	global_store_dwordx4 v[90:91], v[82:85], off offset:16 nt

.LBB0_343:
	s_add_u32 s56, s30, s94
	s_addc_u32 s57, s31, 0
	v_lshl_add_u64 v[74:75], s[56:57], 0, v[78:79]
	v_lshl_add_u64 v[74:75], v[74:75], 0, s[42:43]
	v_lshl_add_u64 v[74:75], v[74:75], 0, v[186:187]
	v_lshl_add_u64 v[78:79], v[74:75], 0, v[176:177]
	v_cvt_pk_bf16_f32 v74, v70, v71
	v_cvt_pk_bf16_f32 v75, v72, v73
	v_cvt_pk_bf16_f32 v76, v66, v67
	v_cvt_pk_bf16_f32 v77, v68, v69
	global_store_dwordx4 v[78:79], v[74:77], off sc0 sc1
	s_and_saveexec_b64 s[60:61], s[14:15]
	s_cbranch_execz .LBB0_345
	s_lshl_b32 s26, s63, 2
	v_lshl_add_u64 v[74:75], v[86:87], 0, s[26:27]
	v_lshlrev_b32_e32 v174, 2, v192
	v_lshl_add_u64 v[74:75], v[74:75], 0, v[174:175]
	global_store_dwordx4 v[74:75], v[70:73], off nt
	global_store_dwordx4 v[74:75], v[66:69], off offset:16 nt

.LBB0_361:
	s_add_u32 s14, s30, s94
	s_addc_u32 s15, s31, 0
	v_lshl_add_u64 v[58:59], s[14:15], 0, v[62:63]
	v_lshl_add_u64 v[58:59], v[58:59], 0, s[42:43]
	v_lshl_add_u64 v[58:59], v[58:59], 0, v[180:181]
	v_lshl_add_u64 v[62:63], v[58:59], 0, v[176:177]
	v_cvt_pk_bf16_f32 v58, v54, v55
	v_cvt_pk_bf16_f32 v59, v56, v57
	v_cvt_pk_bf16_f32 v60, v50, v51
	v_cvt_pk_bf16_f32 v61, v52, v53
	global_store_dwordx4 v[62:63], v[58:61], off sc0 sc1
	s_and_saveexec_b64 s[14:15], s[8:9]
	s_cbranch_execz .LBB0_363
	s_lshl_b32 s26, s63, 2
	v_lshl_add_u64 v[58:59], v[108:109], 0, s[26:27]
	v_lshlrev_b32_e32 v174, 2, v192
	v_lshl_add_u64 v[58:59], v[58:59], 0, v[174:175]
	global_store_dwordx4 v[58:59], v[54:57], off nt
	global_store_dwordx4 v[58:59], v[50:53], off offset:16 nt

.LBB0_377:
	s_add_u32 s14, s30, s94
	s_addc_u32 s15, s31, 0
	v_lshl_add_u64 v[42:43], s[14:15], 0, v[46:47]
	v_lshl_add_u64 v[42:43], v[42:43], 0, s[42:43]
	v_lshl_add_u64 v[42:43], v[42:43], 0, v[186:187]
	v_lshl_add_u64 v[46:47], v[42:43], 0, v[176:177]
	v_cvt_pk_bf16_f32 v42, v38, v39
	v_cvt_pk_bf16_f32 v43, v40, v41
	v_cvt_pk_bf16_f32 v44, v34, v35
	v_cvt_pk_bf16_f32 v45, v36, v37
	global_store_dwordx4 v[46:47], v[42:45], off sc0 sc1
	s_and_saveexec_b64 s[14:15], s[8:9]
	s_cbranch_execz .LBB0_379
	s_lshl_b32 s26, s63, 2
	v_lshl_add_u64 v[42:43], v[54:55], 0, s[26:27]
	v_lshlrev_b32_e32 v174, 2, v192
	v_lshl_add_u64 v[42:43], v[42:43], 0, v[174:175]
	global_store_dwordx4 v[42:43], v[38:41], off nt
	global_store_dwordx4 v[42:43], v[34:37], off offset:16 nt

.LBB0_393:
	s_add_u32 s14, s30, s94
	s_addc_u32 s15, s31, 0
	v_lshl_add_u64 v[26:27], s[14:15], 0, v[30:31]
	v_lshl_add_u64 v[26:27], v[26:27], 0, s[42:43]
	v_lshl_add_u64 v[26:27], v[26:27], 0, v[180:181]
	v_lshl_add_u64 v[30:31], v[26:27], 0, v[176:177]
	v_cvt_pk_bf16_f32 v26, v22, v23
	v_cvt_pk_bf16_f32 v27, v24, v25
	v_cvt_pk_bf16_f32 v28, v18, v19
	v_cvt_pk_bf16_f32 v29, v20, v21
	global_store_dwordx4 v[30:31], v[26:29], off sc0 sc1
	s_and_saveexec_b64 s[14:15], s[8:9]
	s_cbranch_execz .LBB0_395
	s_lshl_b32 s26, s63, 2
	v_lshl_add_u64 v[26:27], v[38:39], 0, s[26:27]
	v_lshlrev_b32_e32 v174, 2, v192
	v_lshl_add_u64 v[26:27], v[26:27], 0, v[174:175]
	global_store_dwordx4 v[26:27], v[22:25], off nt
	global_store_dwordx4 v[26:27], v[18:21], off offset:16 nt

.LBB0_410:
	s_add_u32 s10, s30, s94
	s_addc_u32 s11, s31, 0
	v_lshl_add_u64 v[10:11], s[10:11], 0, v[14:15]
	v_lshl_add_u64 v[10:11], v[10:11], 0, s[42:43]
	v_lshl_add_u64 v[10:11], v[10:11], 0, v[186:187]
	v_lshl_add_u64 v[14:15], v[10:11], 0, v[176:177]
	v_cvt_pk_bf16_f32 v10, v6, v7
	v_cvt_pk_bf16_f32 v11, v8, v9
	v_cvt_pk_bf16_f32 v12, v2, v3
	v_cvt_pk_bf16_f32 v13, v4, v5
	global_store_dwordx4 v[14:15], v[10:13], off sc0 sc1
	s_and_saveexec_b64 s[10:11], s[8:9]
	s_cbranch_execz .LBB0_412
	s_lshl_b32 s26, s63, 2
	v_lshl_add_u64 v[10:11], v[22:23], 0, s[26:27]
	v_lshlrev_b32_e32 v174, 2, v192
	v_lshl_add_u64 v[10:11], v[10:11], 0, v[174:175]
	global_store_dwordx4 v[10:11], v[6:9], off nt
	global_store_dwordx4 v[10:11], v[2:5], off offset:16 nt

.LBB0_647:
	ds_read_b128 v[154:157], v150
	ds_read_b128 v[158:161], v150 offset:1024
	ds_read_b128 v[162:165], v150 offset:2048
	ds_read_b128 v[166:169], v150 offset:3072
	ds_read_b128 v[170:173], v151
	ds_read_b128 v[174:177], v151 offset:1024
	ds_read_b128 v[178:181], v151 offset:2048
	ds_read_b128 v[186:189], v151 offset:3072
	s_add_u32 s40, s38, 0xfffc0080
	s_addc_u32 s41, s39, -1
	s_cmp_eq_u32 s74, 12
	s_cselect_b32 s43, s27, s41
	s_cselect_b32 s42, s68, s40
	s_cselect_b32 s41, s25, s73
	s_cselect_b32 s40, s69, s72
	v_lshl_add_u64 v[146:147], s[38:39], 0, v[138:139]
	s_add_i32 m0, s37, 0xc000
	ds_read_b128 v[190:193], v152
	ds_read_b128 v[194:197], v152 offset:1024
	ds_read_b128 v[198:201], v152 offset:2048
	ds_read_b128 v[202:205], v152 offset:3072
	ds_read_b128 v[206:209], v152 offset:4096
	ds_read_b128 v[210:213], v152 offset:5120
	ds_read_b128 v[214:217], v152 offset:6144
	ds_read_b128 v[218:221], v152 offset:7168
	global_load_lds_dwordx4 v[146:147], off
	v_lshl_add_u64 v[146:147], s[38:39], 0, v[140:141]
	s_add_i32 m0, s37, 0xe000
	s_nop 0
	global_load_lds_dwordx4 v[146:147], off
	s_waitcnt vmcnt(8)
	s_waitcnt lgkmcnt(0)
	s_barrier
	s_setprio 1
	s_waitcnt lgkmcnt(0)
	v_mfma_f32_16x16x32_bf16 v[126:129], v[154:157], v[190:193], v[126:129]
	v_mfma_f32_16x16x32_bf16 v[122:125], v[162:165], v[190:193], v[122:125]
	v_mfma_f32_16x16x32_bf16 v[118:121], v[154:157], v[198:201], v[118:121]
	v_mfma_f32_16x16x32_bf16 v[110:113], v[162:165], v[198:201], v[110:113]
	v_mfma_f32_16x16x32_bf16 v[102:105], v[154:157], v[206:209], v[102:105]
	v_mfma_f32_16x16x32_bf16 v[94:97], v[162:165], v[206:209], v[94:97]
	v_mfma_f32_16x16x32_bf16 v[86:89], v[154:157], v[214:217], v[86:89]
	v_mfma_f32_16x16x32_bf16 v[78:81], v[162:165], v[214:217], v[78:81]
	v_mfma_f32_16x16x32_bf16 v[126:129], v[158:161], v[194:197], v[126:129]
	v_mfma_f32_16x16x32_bf16 v[122:125], v[166:169], v[194:197], v[122:125]
	v_mfma_f32_16x16x32_bf16 v[118:121], v[158:161], v[202:205], v[118:121]
	v_mfma_f32_16x16x32_bf16 v[110:113], v[166:169], v[202:205], v[110:113]
	v_mfma_f32_16x16x32_bf16 v[102:105], v[158:161], v[210:213], v[102:105]
	v_mfma_f32_16x16x32_bf16 v[94:97], v[166:169], v[210:213], v[94:97]
	v_mfma_f32_16x16x32_bf16 v[86:89], v[158:161], v[218:221], v[86:89]
	v_mfma_f32_16x16x32_bf16 v[78:81], v[166:169], v[218:221], v[78:81]
	s_setprio 0
	s_setprio 1
	v_mfma_f32_16x16x32_bf16 v[114:117], v[170:173], v[190:193], v[114:117]
	v_mfma_f32_16x16x32_bf16 v[106:109], v[178:181], v[190:193], v[106:109]
	v_mfma_f32_16x16x32_bf16 v[98:101], v[170:173], v[198:201], v[98:101]
	v_mfma_f32_16x16x32_bf16 v[90:93], v[178:181], v[198:201], v[90:93]
	v_mfma_f32_16x16x32_bf16 v[82:85], v[170:173], v[206:209], v[82:85]
	v_mfma_f32_16x16x32_bf16 v[74:77], v[178:181], v[206:209], v[74:77]
	v_mfma_f32_16x16x32_bf16 v[70:73], v[170:173], v[214:217], v[70:73]
	v_mfma_f32_16x16x32_bf16 v[66:69], v[178:181], v[214:217], v[66:69]
	v_mfma_f32_16x16x32_bf16 v[114:117], v[174:177], v[194:197], v[114:117]
	v_mfma_f32_16x16x32_bf16 v[106:109], v[186:189], v[194:197], v[106:109]
	v_mfma_f32_16x16x32_bf16 v[98:101], v[174:177], v[202:205], v[98:101]
	v_mfma_f32_16x16x32_bf16 v[90:93], v[186:189], v[202:205], v[90:93]
	v_mfma_f32_16x16x32_bf16 v[82:85], v[174:177], v[210:213], v[82:85]
	v_mfma_f32_16x16x32_bf16 v[74:77], v[186:189], v[210:213], v[74:77]
	v_mfma_f32_16x16x32_bf16 v[70:73], v[174:177], v[218:221], v[70:73]
	v_mfma_f32_16x16x32_bf16 v[66:69], v[186:189], v[218:221], v[66:69]
	s_setprio 0
	s_barrier
	s_add_i32 s54, s60, s45
	v_lshl_add_u64 v[146:147], s[40:41], 0, v[132:133]
	s_mov_b32 m0, s54
	ds_read_b128 v[190:193], v152 offset:16384
	ds_read_b128 v[194:197], v152 offset:17408
	ds_read_b128 v[198:201], v152 offset:18432
	ds_read_b128 v[202:205], v152 offset:19456
	ds_read_b128 v[206:209], v152 offset:20480
	ds_read_b128 v[210:213], v152 offset:21504
	ds_read_b128 v[214:217], v152 offset:22528
	ds_read_b128 v[218:221], v152 offset:23552
	global_load_lds_dwordx4 v[146:147], off
	s_add_i32 m0, s54, 0x2000
	s_add_u32 s54, s40, 0x40000
	v_lshl_add_u64 v[182:183], s[40:41], 0, v[136:137]
	s_addc_u32 s55, s41, 0
	s_add_i32 s56, s61, s45
	global_load_lds_dwordx4 v[182:183], off
	v_lshl_add_u64 v[222:223], s[54:55], 0, v[132:133]
	s_mov_b32 m0, s56
	v_lshl_add_u64 v[224:225], s[42:43], 0, v[134:135]
	global_load_lds_dwordx4 v[222:223], off
	v_lshl_add_u64 v[222:223], s[54:55], 0, v[136:137]
	s_add_i32 m0, s56, 0x2000
	s_nop 0
	global_load_lds_dwordx4 v[222:223], off
	v_lshl_add_u64 v[222:223], s[42:43], 0, v[130:131]
	s_mov_b32 m0, s37
	s_nop 0
	global_load_lds_dwordx4 v[222:223], off
	s_mov_b32 m0, s47
	s_nop 0
	global_load_lds_dwordx4 v[224:225], off
	s_waitcnt vmcnt(8)
	s_waitcnt lgkmcnt(0)
	s_barrier
	s_setprio 1
	s_waitcnt lgkmcnt(0)
	v_mfma_f32_16x16x32_bf16 v[62:65], v[154:157], v[190:193], v[62:65]
	v_mfma_f32_16x16x32_bf16 v[58:61], v[162:165], v[190:193], v[58:61]
	v_mfma_f32_16x16x32_bf16 v[54:57], v[154:157], v[198:201], v[54:57]
	v_mfma_f32_16x16x32_bf16 v[46:49], v[162:165], v[198:201], v[46:49]
	v_mfma_f32_16x16x32_bf16 v[38:41], v[154:157], v[206:209], v[38:41]
	v_mfma_f32_16x16x32_bf16 v[30:33], v[162:165], v[206:209], v[30:33]
	v_mfma_f32_16x16x32_bf16 v[22:25], v[154:157], v[214:217], v[22:25]
	v_mfma_f32_16x16x32_bf16 v[14:17], v[162:165], v[214:217], v[14:17]
	v_mfma_f32_16x16x32_bf16 v[62:65], v[158:161], v[194:197], v[62:65]
	v_mfma_f32_16x16x32_bf16 v[58:61], v[166:169], v[194:197], v[58:61]
	v_mfma_f32_16x16x32_bf16 v[54:57], v[158:161], v[202:205], v[54:57]
	v_mfma_f32_16x16x32_bf16 v[46:49], v[166:169], v[202:205], v[46:49]
	v_mfma_f32_16x16x32_bf16 v[38:41], v[158:161], v[210:213], v[38:41]
	v_mfma_f32_16x16x32_bf16 v[30:33], v[166:169], v[210:213], v[30:33]
	v_mfma_f32_16x16x32_bf16 v[22:25], v[158:161], v[218:221], v[22:25]
	v_mfma_f32_16x16x32_bf16 v[14:17], v[166:169], v[218:221], v[14:17]
	s_setprio 0
	s_setprio 1
	v_mfma_f32_16x16x32_bf16 v[50:53], v[170:173], v[190:193], v[50:53]
	v_mfma_f32_16x16x32_bf16 v[42:45], v[178:181], v[190:193], v[42:45]
	v_mfma_f32_16x16x32_bf16 v[34:37], v[170:173], v[198:201], v[34:37]
	v_mfma_f32_16x16x32_bf16 v[26:29], v[178:181], v[198:201], v[26:29]
	v_mfma_f32_16x16x32_bf16 v[18:21], v[170:173], v[206:209], v[18:21]
	v_mfma_f32_16x16x32_bf16 v[10:13], v[178:181], v[206:209], v[10:13]
	v_mfma_f32_16x16x32_bf16 v[6:9], v[170:173], v[214:217], v[6:9]
	v_mfma_f32_16x16x32_bf16 v[2:5], v[178:181], v[214:217], v[2:5]
	v_mfma_f32_16x16x32_bf16 v[50:53], v[174:177], v[194:197], v[50:53]
	v_mfma_f32_16x16x32_bf16 v[42:45], v[186:189], v[194:197], v[42:45]
	v_mfma_f32_16x16x32_bf16 v[34:37], v[174:177], v[202:205], v[34:37]
	v_mfma_f32_16x16x32_bf16 v[26:29], v[186:189], v[202:205], v[26:29]
	v_mfma_f32_16x16x32_bf16 v[18:21], v[174:177], v[210:213], v[18:21]
	v_mfma_f32_16x16x32_bf16 v[10:13], v[186:189], v[210:213], v[10:13]
	v_mfma_f32_16x16x32_bf16 v[6:9], v[174:177], v[218:221], v[6:9]
	v_mfma_f32_16x16x32_bf16 v[2:5], v[186:189], v[218:221], v[2:5]
	s_setprio 0
	s_barrier
	s_add_i32 s54, 0, 0x18000
	v_add_u32_e32 v153, s54, v148
	s_add_i32 s55, 0, 0x1c000
	ds_read_b128 v[154:157], v153
	ds_read_b128 v[158:161], v153 offset:1024
	ds_read_b128 v[162:165], v153 offset:2048
	ds_read_b128 v[166:169], v153 offset:3072
	v_add_u32_e32 v153, s55, v148
	ds_read_b128 v[170:173], v153
	ds_read_b128 v[174:177], v153 offset:1024
	ds_read_b128 v[178:181], v153 offset:2048
	ds_read_b128 v[186:189], v153 offset:3072
	s_add_u32 s42, s42, 0x40000
	s_addc_u32 s43, s43, 0
	s_mov_b32 m0, s48
	v_lshl_add_u64 v[226:227], s[42:43], 0, v[130:131]
	ds_read_b128 v[190:193], v152 offset:32768
	ds_read_b128 v[194:197], v152 offset:33792
	ds_read_b128 v[198:201], v152 offset:34816
	ds_read_b128 v[202:205], v152 offset:35840
	ds_read_b128 v[206:209], v152 offset:36864
	ds_read_b128 v[210:213], v152 offset:37888
	ds_read_b128 v[214:217], v152 offset:38912
	ds_read_b128 v[218:221], v152 offset:39936
	global_load_lds_dwordx4 v[226:227], off
	v_lshl_add_u64 v[226:227], s[42:43], 0, v[134:135]
	s_mov_b32 m0, s49
	s_nop 0
	global_load_lds_dwordx4 v[226:227], off
	s_waitcnt vmcnt(8)
	s_waitcnt lgkmcnt(0)
	s_barrier
	s_setprio 1
	s_waitcnt lgkmcnt(0)
	v_mfma_f32_16x16x32_bf16 v[126:129], v[154:157], v[190:193], v[126:129]
	v_mfma_f32_16x16x32_bf16 v[122:125], v[162:165], v[190:193], v[122:125]
	v_mfma_f32_16x16x32_bf16 v[118:121], v[154:157], v[198:201], v[118:121]
	v_mfma_f32_16x16x32_bf16 v[110:113], v[162:165], v[198:201], v[110:113]
	v_mfma_f32_16x16x32_bf16 v[102:105], v[154:157], v[206:209], v[102:105]
	v_mfma_f32_16x16x32_bf16 v[94:97], v[162:165], v[206:209], v[94:97]
	v_mfma_f32_16x16x32_bf16 v[86:89], v[154:157], v[214:217], v[86:89]
	v_mfma_f32_16x16x32_bf16 v[78:81], v[162:165], v[214:217], v[78:81]
	v_mfma_f32_16x16x32_bf16 v[126:129], v[158:161], v[194:197], v[126:129]
	v_mfma_f32_16x16x32_bf16 v[122:125], v[166:169], v[194:197], v[122:125]
	v_mfma_f32_16x16x32_bf16 v[118:121], v[158:161], v[202:205], v[118:121]
	v_mfma_f32_16x16x32_bf16 v[110:113], v[166:169], v[202:205], v[110:113]
	v_mfma_f32_16x16x32_bf16 v[102:105], v[158:161], v[210:213], v[102:105]
	v_mfma_f32_16x16x32_bf16 v[94:97], v[166:169], v[210:213], v[94:97]
	v_mfma_f32_16x16x32_bf16 v[86:89], v[158:161], v[218:221], v[86:89]
	v_mfma_f32_16x16x32_bf16 v[78:81], v[166:169], v[218:221], v[78:81]
	s_setprio 0
	s_setprio 1
	v_mfma_f32_16x16x32_bf16 v[114:117], v[170:173], v[190:193], v[114:117]
	v_mfma_f32_16x16x32_bf16 v[106:109], v[178:181], v[190:193], v[106:109]
	v_mfma_f32_16x16x32_bf16 v[98:101], v[170:173], v[198:201], v[98:101]
	v_mfma_f32_16x16x32_bf16 v[90:93], v[178:181], v[198:201], v[90:93]
	v_mfma_f32_16x16x32_bf16 v[82:85], v[170:173], v[206:209], v[82:85]
	v_mfma_f32_16x16x32_bf16 v[74:77], v[178:181], v[206:209], v[74:77]
	v_mfma_f32_16x16x32_bf16 v[70:73], v[170:173], v[214:217], v[70:73]
	v_mfma_f32_16x16x32_bf16 v[66:69], v[178:181], v[214:217], v[66:69]
	v_mfma_f32_16x16x32_bf16 v[114:117], v[174:177], v[194:197], v[114:117]
	v_mfma_f32_16x16x32_bf16 v[106:109], v[186:189], v[194:197], v[106:109]
	v_mfma_f32_16x16x32_bf16 v[98:101], v[174:177], v[202:205], v[98:101]
	v_mfma_f32_16x16x32_bf16 v[90:93], v[186:189], v[202:205], v[90:93]
	v_mfma_f32_16x16x32_bf16 v[82:85], v[174:177], v[210:213], v[82:85]
	v_mfma_f32_16x16x32_bf16 v[74:77], v[186:189], v[210:213], v[74:77]
	v_mfma_f32_16x16x32_bf16 v[70:73], v[174:177], v[218:221], v[70:73]
	v_mfma_f32_16x16x32_bf16 v[66:69], v[186:189], v[218:221], v[66:69]
	s_setprio 0
	s_barrier
	s_add_i32 s42, s54, s45
	v_lshl_add_u64 v[146:147], v[146:147], 0, s[14:15]
	s_mov_b32 m0, s42
	ds_read_b128 v[190:193], v152 offset:49152
	ds_read_b128 v[194:197], v152 offset:50176
	ds_read_b128 v[198:201], v152 offset:51200
	ds_read_b128 v[202:205], v152 offset:52224
	ds_read_b128 v[206:209], v152 offset:53248
	ds_read_b128 v[210:213], v152 offset:54272
	ds_read_b128 v[214:217], v152 offset:55296
	ds_read_b128 v[218:221], v152 offset:56320
	global_load_lds_dwordx4 v[146:147], off
	s_add_i32 m0, s42, 0x2000
	s_add_u32 s40, s40, 0x40080
	v_lshl_add_u64 v[146:147], v[182:183], 0, s[14:15]
	s_addc_u32 s41, s41, 0
	s_add_i32 s42, s55, s45
	global_load_lds_dwordx4 v[146:147], off
	v_lshl_add_u64 v[146:147], s[40:41], 0, v[132:133]
	s_mov_b32 m0, s42
	s_nop 0
	global_load_lds_dwordx4 v[146:147], off
	v_lshl_add_u64 v[146:147], s[40:41], 0, v[136:137]
	s_add_i32 m0, s42, 0x2000
	s_nop 0
	global_load_lds_dwordx4 v[146:147], off
	v_lshl_add_u64 v[146:147], v[222:223], 0, s[14:15]
	s_mov_b32 m0, s58
	s_nop 0
	global_load_lds_dwordx4 v[146:147], off
	v_lshl_add_u64 v[146:147], v[224:225], 0, s[14:15]
	s_mov_b32 m0, s59
	s_nop 0
	global_load_lds_dwordx4 v[146:147], off
	s_waitcnt vmcnt(8)
	s_waitcnt lgkmcnt(0)
	s_barrier
	s_setprio 1
	s_waitcnt lgkmcnt(0)
	v_mfma_f32_16x16x32_bf16 v[62:65], v[154:157], v[190:193], v[62:65]
	v_mfma_f32_16x16x32_bf16 v[58:61], v[162:165], v[190:193], v[58:61]
	v_mfma_f32_16x16x32_bf16 v[54:57], v[154:157], v[198:201], v[54:57]
	v_mfma_f32_16x16x32_bf16 v[46:49], v[162:165], v[198:201], v[46:49]
	v_mfma_f32_16x16x32_bf16 v[38:41], v[154:157], v[206:209], v[38:41]
	v_mfma_f32_16x16x32_bf16 v[30:33], v[162:165], v[206:209], v[30:33]
	v_mfma_f32_16x16x32_bf16 v[22:25], v[154:157], v[214:217], v[22:25]
	v_mfma_f32_16x16x32_bf16 v[14:17], v[162:165], v[214:217], v[14:17]
	v_mfma_f32_16x16x32_bf16 v[62:65], v[158:161], v[194:197], v[62:65]
	v_mfma_f32_16x16x32_bf16 v[58:61], v[166:169], v[194:197], v[58:61]
	v_mfma_f32_16x16x32_bf16 v[54:57], v[158:161], v[202:205], v[54:57]
	v_mfma_f32_16x16x32_bf16 v[46:49], v[166:169], v[202:205], v[46:49]
	v_mfma_f32_16x16x32_bf16 v[38:41], v[158:161], v[210:213], v[38:41]
	v_mfma_f32_16x16x32_bf16 v[30:33], v[166:169], v[210:213], v[30:33]
	v_mfma_f32_16x16x32_bf16 v[22:25], v[158:161], v[218:221], v[22:25]
	v_mfma_f32_16x16x32_bf16 v[14:17], v[166:169], v[218:221], v[14:17]
	s_setprio 0
	s_setprio 1
	v_mfma_f32_16x16x32_bf16 v[50:53], v[170:173], v[190:193], v[50:53]
	v_mfma_f32_16x16x32_bf16 v[42:45], v[178:181], v[190:193], v[42:45]
	v_mfma_f32_16x16x32_bf16 v[34:37], v[170:173], v[198:201], v[34:37]
	v_mfma_f32_16x16x32_bf16 v[26:29], v[178:181], v[198:201], v[26:29]
	v_mfma_f32_16x16x32_bf16 v[18:21], v[170:173], v[206:209], v[18:21]
	v_mfma_f32_16x16x32_bf16 v[10:13], v[178:181], v[206:209], v[10:13]
	v_mfma_f32_16x16x32_bf16 v[6:9], v[170:173], v[214:217], v[6:9]
	v_mfma_f32_16x16x32_bf16 v[2:5], v[178:181], v[214:217], v[2:5]
	v_mfma_f32_16x16x32_bf16 v[50:53], v[174:177], v[194:197], v[50:53]
	v_mfma_f32_16x16x32_bf16 v[42:45], v[186:189], v[194:197], v[42:45]
	v_mfma_f32_16x16x32_bf16 v[34:37], v[174:177], v[202:205], v[34:37]
	v_mfma_f32_16x16x32_bf16 v[26:29], v[186:189], v[202:205], v[26:29]
	v_mfma_f32_16x16x32_bf16 v[18:21], v[174:177], v[210:213], v[18:21]
	v_mfma_f32_16x16x32_bf16 v[10:13], v[186:189], v[210:213], v[10:13]
	v_mfma_f32_16x16x32_bf16 v[6:9], v[174:177], v[218:221], v[6:9]
	v_mfma_f32_16x16x32_bf16 v[2:5], v[186:189], v[218:221], v[2:5]
	s_setprio 0
	s_barrier
	s_add_i32 s74, s74, 2
	s_add_u32 s72, s72, 0x100
	s_addc_u32 s73, s73, 0
	s_add_u32 s38, s38, 0x100
	s_addc_u32 s39, s39, 0
	s_cmp_gt_u32 s74, 13
	s_cbranch_scc0 .LBB0_647
	v_lshl_add_u32 v154, s36, 8, v1
	v_lshl_or_b32 v146, s67, 8, v149
	v_ashrrev_i32_e32 v155, 31, v154
	v_ashrrev_i32_e32 v147, 31, v146
	v_lshlrev_b64 v[156:157], 11, v[154:155]
	v_lshl_add_u64 v[156:157], s[6:7], 0, v[156:157]
	v_lshlrev_b64 v[158:159], 1, v[146:147]
	v_lshl_add_u64 v[146:147], v[156:157], 0, v[158:159]
	v_cvt_pk_bf16_f32 v126, v126, v127
	v_cvt_pk_bf16_f32 v127, v128, v129
	v_cvt_pk_bf16_f32 v128, v122, v123
	v_cvt_pk_bf16_f32 v129, v124, v125
	global_store_dwordx4 v[146:147], v[126:129], off sc0 sc1
	v_cvt_pk_bf16_f32 v114, v114, v115
	v_cvt_pk_bf16_f32 v115, v116, v117
	v_cvt_pk_bf16_f32 v116, v106, v107
	v_or_b32_e32 v106, 16, v154
	v_ashrrev_i32_e32 v107, 31, v106
	v_lshlrev_b64 v[106:107], 11, v[106:107]
	v_lshl_add_u64 v[106:107], s[6:7], 0, v[106:107]
	v_cvt_pk_bf16_f32 v117, v108, v109
	global_store_dwordx4 v[146:147], v[114:117], off offset:256 sc0 sc1
	s_mov_b32 s67, s24
	s_mov_b32 s36, s26
	v_lshl_add_u64 v[114:115], v[106:107], 0, v[158:159]
	v_cvt_pk_bf16_f32 v106, v118, v119
	v_cvt_pk_bf16_f32 v107, v120, v121
	v_cvt_pk_bf16_f32 v108, v110, v111
	v_cvt_pk_bf16_f32 v109, v112, v113
	global_store_dwordx4 v[114:115], v[106:109], off sc0 sc1
	v_cvt_pk_bf16_f32 v98, v98, v99
	v_cvt_pk_bf16_f32 v99, v100, v101
	v_cvt_pk_bf16_f32 v100, v90, v91
	v_or_b32_e32 v90, 32, v154
	v_ashrrev_i32_e32 v91, 31, v90
	v_lshlrev_b64 v[90:91], 11, v[90:91]
	v_lshl_add_u64 v[90:91], s[6:7], 0, v[90:91]
	v_cvt_pk_bf16_f32 v101, v92, v93
	global_store_dwordx4 v[114:115], v[98:101], off offset:256 sc0 sc1
	s_mov_b64 s[38:39], s[30:31]
	s_mov_b64 s[40:41], s[28:29]
	v_lshl_add_u64 v[98:99], v[90:91], 0, v[158:159]
	v_cvt_pk_bf16_f32 v90, v102, v103
	v_cvt_pk_bf16_f32 v91, v104, v105
	v_cvt_pk_bf16_f32 v92, v94, v95
	v_cvt_pk_bf16_f32 v93, v96, v97
	global_store_dwordx4 v[98:99], v[90:93], off sc0 sc1
	v_cvt_pk_bf16_f32 v82, v82, v83
	v_cvt_pk_bf16_f32 v83, v84, v85
	v_cvt_pk_bf16_f32 v84, v74, v75
	v_or_b32_e32 v74, 48, v154
	v_ashrrev_i32_e32 v75, 31, v74
	v_lshlrev_b64 v[74:75], 11, v[74:75]
	v_lshl_add_u64 v[74:75], s[6:7], 0, v[74:75]
	v_cvt_pk_bf16_f32 v85, v76, v77
	global_store_dwordx4 v[98:99], v[82:85], off offset:256 sc0 sc1
	s_nop 1
	v_lshl_add_u64 v[82:83], v[74:75], 0, v[158:159]
	v_cvt_pk_bf16_f32 v74, v86, v87
	v_cvt_pk_bf16_f32 v75, v88, v89
	v_cvt_pk_bf16_f32 v76, v78, v79
	v_cvt_pk_bf16_f32 v77, v80, v81
	global_store_dwordx4 v[82:83], v[74:77], off sc0 sc1
	v_cvt_pk_bf16_f32 v70, v70, v71
	v_cvt_pk_bf16_f32 v71, v72, v73
	v_cvt_pk_bf16_f32 v72, v66, v67
	v_cvt_pk_bf16_f32 v73, v68, v69
	global_store_dwordx4 v[82:83], v[70:73], off offset:256 sc0 sc1
	v_cvt_pk_bf16_f32 v62, v62, v63
	v_cvt_pk_bf16_f32 v63, v64, v65
	v_cvt_pk_bf16_f32 v64, v58, v59
	v_add_co_u32_e32 v58, vcc, s62, v146
	v_lshl_add_u64 v[66:67], v[146:147], 0, s[12:13]
	s_nop 0
	v_addc_co_u32_e32 v59, vcc, 0, v147, vcc
	v_cvt_pk_bf16_f32 v65, v60, v61
	global_store_dwordx4 v[58:59], v[62:65], off sc0 sc1
	v_cvt_pk_bf16_f32 v50, v50, v51
	v_cvt_pk_bf16_f32 v51, v52, v53
	v_cvt_pk_bf16_f32 v52, v42, v43
	v_cvt_pk_bf16_f32 v53, v44, v45
	global_store_dwordx4 v[66:67], v[50:53], off offset:256 sc0 sc1
	v_cvt_pk_bf16_f32 v42, v54, v55
	v_cvt_pk_bf16_f32 v43, v56, v57
	v_cvt_pk_bf16_f32 v44, v46, v47
	v_add_co_u32_e32 v46, vcc, s63, v146
	s_nop 0
	v_lshl_add_u64 v[50:51], v[146:147], 0, s[16:17]
	v_addc_co_u32_e32 v47, vcc, 0, v147, vcc
	v_cvt_pk_bf16_f32 v45, v48, v49
	global_store_dwordx4 v[46:47], v[42:45], off sc0 sc1
	v_cvt_pk_bf16_f32 v34, v34, v35
	v_cvt_pk_bf16_f32 v35, v36, v37
	v_cvt_pk_bf16_f32 v36, v26, v27
	v_cvt_pk_bf16_f32 v37, v28, v29
	global_store_dwordx4 v[50:51], v[34:37], off offset:256 sc0 sc1
	v_cvt_pk_bf16_f32 v26, v38, v39
	v_cvt_pk_bf16_f32 v27, v40, v41
	v_cvt_pk_bf16_f32 v28, v30, v31
	v_add_co_u32_e32 v30, vcc, s64, v146
	s_nop 0
	v_lshl_add_u64 v[34:35], v[146:147], 0, s[18:19]
	v_addc_co_u32_e32 v31, vcc, 0, v147, vcc
	v_cvt_pk_bf16_f32 v29, v32, v33
	global_store_dwordx4 v[30:31], v[26:29], off sc0 sc1
	v_cvt_pk_bf16_f32 v18, v18, v19
	v_cvt_pk_bf16_f32 v19, v20, v21
	v_cvt_pk_bf16_f32 v20, v10, v11
	v_cvt_pk_bf16_f32 v21, v12, v13
	global_store_dwordx4 v[34:35], v[18:21], off offset:256 sc0 sc1
	v_cvt_pk_bf16_f32 v10, v22, v23
	v_cvt_pk_bf16_f32 v11, v24, v25
	v_cvt_pk_bf16_f32 v12, v14, v15
	v_add_co_u32_e32 v14, vcc, s66, v146
	s_nop 0
	v_lshl_add_u64 v[18:19], v[146:147], 0, s[20:21]
	v_addc_co_u32_e32 v15, vcc, 0, v147, vcc
	s_and_b64 vcc, exec, s[4:5]
	v_cvt_pk_bf16_f32 v13, v16, v17
	global_store_dwordx4 v[14:15], v[10:13], off sc0 sc1
	v_cvt_pk_bf16_f32 v6, v6, v7
	v_cvt_pk_bf16_f32 v7, v8, v9
	v_cvt_pk_bf16_f32 v8, v2, v3
	v_cvt_pk_bf16_f32 v9, v4, v5
	global_store_dwordx4 v[18:19], v[6:9], off offset:256 sc0 sc1
	s_cbranch_vccz .LBB0_640
	s_waitcnt vmcnt(0)
	s_cmpk_gt_u32 s44, 0xff
	s_cbranch_scc1 .LBB0_651
	s_barrier

.LBB0_806:
	v_lshl_add_u64 v[10:11], v[18:19], 0, s[24:25]
	v_cvt_pk_bf16_f32 v6, v6, v7
	v_cvt_pk_bf16_f32 v7, v8, v9
	v_cvt_pk_bf16_f32 v8, v2, v3
	v_add_co_u32_e32 v2, vcc, 0x840000, v10
	s_mov_b32 s6, s26
	s_nop 0
	v_addc_co_u32_e32 v3, vcc, 0, v11, vcc
	s_and_b64 vcc, exec, s[4:5]
	s_mov_b32 s38, s28
	s_mov_b64 s[42:43], s[36:37]
	s_mov_b64 s[40:41], s[30:31]
	v_cvt_pk_bf16_f32 v9, v4, v5
	global_store_dwordx4 v[2:3], v[6:9], off sc0 sc1
	s_cbranch_vccnz .LBB0_847

.LBB0_817:
	s_and_b64 s[42:43], s[40:41], exec
	s_cselect_b32 s7, s66, 0x9700000
	s_add_u32 s7, s8, s7
	s_addc_u32 s27, s9, 0
	s_lshl_b32 s6, s6, 2
	s_and_b32 s6, s6, 12
	s_or_b32 s6, s6, s62
	s_mul_i32 s6, s6, 0x420000
	s_add_u32 s6, s7, s6
	s_addc_u32 s7, s27, 0
	v_lshl_add_u32 v148, s38, 8, v1
	s_add_u32 s6, s6, s67
	s_addc_u32 s7, s7, 0
	v_ashrrev_i32_e32 v149, 31, v148
	v_lshl_add_u64 v[150:151], s[6:7], 0, v[138:139]
	v_lshlrev_b64 v[152:153], 7, v[148:149]
	v_cvt_pk_bf16_f32 v126, v126, v127
	v_cvt_pk_bf16_f32 v127, v128, v129
	v_cvt_pk_bf16_f32 v128, v122, v123
	v_cndmask_b32_e64 v122, 0, 1, s[40:41]
	v_lshl_add_u64 v[152:153], v[150:151], 0, v[152:153]
	v_cmp_ne_u32_e64 s[6:7], 1, v122
	s_andn2_b64 vcc, exec, s[40:41]
	v_cvt_pk_bf16_f32 v129, v124, v125
	global_store_dwordx4 v[152:153], v[126:129], off sc0 sc1
	s_cbranch_vccnz .LBB0_819
	v_mul_f32_e32 v122, 0xbfb8aa3b, v118
	v_mul_f32_e32 v123, 0xbfb8aa3b, v119
	v_mul_f32_e32 v124, 0xbfb8aa3b, v120
	v_mul_f32_e32 v125, 0xbfb8aa3b, v121
	v_mul_f32_e32 v126, 0xbfb8aa3b, v114
	v_mul_f32_e32 v127, 0xbfb8aa3b, v115
	v_mul_f32_e32 v128, 0xbfb8aa3b, v116
	v_mul_f32_e32 v129, 0xbfb8aa3b, v117
	v_exp_f32_e32 v122, v122
	v_exp_f32_e32 v123, v123
	v_exp_f32_e32 v124, v124
	v_exp_f32_e32 v125, v125
	v_exp_f32_e32 v126, v126
	v_exp_f32_e32 v127, v127
	v_exp_f32_e32 v128, v128
	v_exp_f32_e32 v129, v129
	v_add_f32_e32 v122, 1.0, v122
	v_add_f32_e32 v123, 1.0, v123
	v_add_f32_e32 v124, 1.0, v124
	v_add_f32_e32 v125, 1.0, v125
	v_add_f32_e32 v126, 1.0, v126
	v_add_f32_e32 v127, 1.0, v127
	v_add_f32_e32 v128, 1.0, v128
	v_add_f32_e32 v129, 1.0, v129
	v_rcp_f32_e32 v122, v122
	v_rcp_f32_e32 v123, v123
	v_rcp_f32_e32 v124, v124
	v_rcp_f32_e32 v125, v125
	v_rcp_f32_e32 v126, v126
	v_rcp_f32_e32 v128, v128
	v_rcp_f32_e32 v129, v129
	v_rcp_f32_e32 v127, v127
	v_pk_mul_f32 v[120:121], v[120:121], v[124:125]
	v_pk_mul_f32 v[118:119], v[118:119], v[122:123]
	v_pk_mul_f32 v[116:117], v[116:117], v[128:129]
	v_pk_mul_f32 v[114:115], v[114:115], v[126:127]
.LBB0_819:
	v_cvt_pk_bf16_f32 v118, v118, v119
	v_cvt_pk_bf16_f32 v119, v120, v121
	s_nop 0
	v_cvt_pk_bf16_f32 v120, v114, v115
	v_add_co_u32_e32 v114, vcc, 0x840000, v152
	v_cvt_pk_bf16_f32 v121, v116, v117
	s_nop 1
	v_addc_co_u32_e32 v115, vcc, 0, v153, vcc
	s_and_b64 vcc, exec, s[6:7]
	global_store_dwordx4 v[114:115], v[118:121], off sc0 sc1
	s_cbranch_vccnz .LBB0_821
	v_mul_f32_e32 v114, 0xbfb8aa3b, v110
	v_mul_f32_e32 v115, 0xbfb8aa3b, v111
	v_mul_f32_e32 v116, 0xbfb8aa3b, v112
	v_mul_f32_e32 v117, 0xbfb8aa3b, v113
	v_mul_f32_e32 v118, 0xbfb8aa3b, v106
	v_mul_f32_e32 v119, 0xbfb8aa3b, v107
	v_mul_f32_e32 v120, 0xbfb8aa3b, v108
	v_mul_f32_e32 v121, 0xbfb8aa3b, v109
	v_exp_f32_e32 v114, v114
	v_exp_f32_e32 v115, v115
	v_exp_f32_e32 v116, v116
	v_exp_f32_e32 v117, v117
	v_exp_f32_e32 v118, v118
	v_exp_f32_e32 v119, v119
	v_exp_f32_e32 v120, v120
	v_exp_f32_e32 v121, v121
	v_add_f32_e32 v114, 1.0, v114
	v_add_f32_e32 v115, 1.0, v115
	v_add_f32_e32 v116, 1.0, v116
	v_add_f32_e32 v117, 1.0, v117
	v_add_f32_e32 v118, 1.0, v118
	v_add_f32_e32 v119, 1.0, v119
	v_add_f32_e32 v120, 1.0, v120
	v_add_f32_e32 v121, 1.0, v121
	v_rcp_f32_e32 v114, v114
	v_rcp_f32_e32 v115, v115
	v_rcp_f32_e32 v116, v116
	v_rcp_f32_e32 v117, v117
	v_rcp_f32_e32 v118, v118
	v_rcp_f32_e32 v120, v120
	v_rcp_f32_e32 v121, v121
	v_rcp_f32_e32 v119, v119
	v_pk_mul_f32 v[112:113], v[112:113], v[116:117]
	v_pk_mul_f32 v[110:111], v[110:111], v[114:115]
	v_pk_mul_f32 v[108:109], v[108:109], v[120:121]
	v_pk_mul_f32 v[106:107], v[106:107], v[118:119]
.LBB0_821:
	v_or_b32_e32 v114, 16, v148
	v_ashrrev_i32_e32 v115, 31, v114
	v_lshlrev_b64 v[114:115], 7, v[114:115]
	v_lshl_add_u64 v[114:115], v[150:151], 0, v[114:115]
	s_and_b64 vcc, exec, s[6:7]
	v_cvt_pk_bf16_f32 v110, v110, v111
	v_cvt_pk_bf16_f32 v111, v112, v113
	v_cvt_pk_bf16_f32 v112, v106, v107
	v_cvt_pk_bf16_f32 v113, v108, v109
	global_store_dwordx4 v[114:115], v[110:113], off sc0 sc1
	s_cbranch_vccnz .LBB0_823
	v_mul_f32_e32 v106, 0xbfb8aa3b, v102
	v_mul_f32_e32 v107, 0xbfb8aa3b, v103
	v_mul_f32_e32 v108, 0xbfb8aa3b, v104
	v_mul_f32_e32 v109, 0xbfb8aa3b, v105
	v_mul_f32_e32 v110, 0xbfb8aa3b, v98
	v_mul_f32_e32 v111, 0xbfb8aa3b, v99
	v_mul_f32_e32 v112, 0xbfb8aa3b, v100
	v_mul_f32_e32 v113, 0xbfb8aa3b, v101
	v_exp_f32_e32 v106, v106
	v_exp_f32_e32 v107, v107
	v_exp_f32_e32 v108, v108
	v_exp_f32_e32 v109, v109
	v_exp_f32_e32 v110, v110
	v_exp_f32_e32 v111, v111
	v_exp_f32_e32 v112, v112
	v_exp_f32_e32 v113, v113
	v_add_f32_e32 v106, 1.0, v106
	v_add_f32_e32 v107, 1.0, v107
	v_add_f32_e32 v108, 1.0, v108
	v_add_f32_e32 v109, 1.0, v109
	v_add_f32_e32 v110, 1.0, v110
	v_add_f32_e32 v111, 1.0, v111
	v_add_f32_e32 v112, 1.0, v112
	v_add_f32_e32 v113, 1.0, v113
	v_rcp_f32_e32 v106, v106
	v_rcp_f32_e32 v107, v107
	v_rcp_f32_e32 v108, v108
	v_rcp_f32_e32 v109, v109
	v_rcp_f32_e32 v110, v110
	v_rcp_f32_e32 v112, v112
	v_rcp_f32_e32 v113, v113
	v_rcp_f32_e32 v111, v111
	v_pk_mul_f32 v[104:105], v[104:105], v[108:109]
	v_pk_mul_f32 v[102:103], v[102:103], v[106:107]
	v_pk_mul_f32 v[100:101], v[100:101], v[112:113]
	v_pk_mul_f32 v[98:99], v[98:99], v[110:111]
.LBB0_823:
	v_cvt_pk_bf16_f32 v102, v102, v103
	v_cvt_pk_bf16_f32 v103, v104, v105
	s_nop 0
	v_cvt_pk_bf16_f32 v104, v98, v99
	v_add_co_u32_e32 v98, vcc, 0x840000, v114
	v_cvt_pk_bf16_f32 v105, v100, v101
	s_nop 1
	v_addc_co_u32_e32 v99, vcc, 0, v115, vcc
	s_and_b64 vcc, exec, s[6:7]
	global_store_dwordx4 v[98:99], v[102:105], off sc0 sc1
	s_cbranch_vccnz .LBB0_825
	v_mul_f32_e32 v98, 0xbfb8aa3b, v94
	v_mul_f32_e32 v99, 0xbfb8aa3b, v95
	v_mul_f32_e32 v100, 0xbfb8aa3b, v96
	v_mul_f32_e32 v101, 0xbfb8aa3b, v97
	v_mul_f32_e32 v102, 0xbfb8aa3b, v90
	v_mul_f32_e32 v103, 0xbfb8aa3b, v91
	v_mul_f32_e32 v104, 0xbfb8aa3b, v92
	v_mul_f32_e32 v105, 0xbfb8aa3b, v93
	v_exp_f32_e32 v98, v98
	v_exp_f32_e32 v99, v99
	v_exp_f32_e32 v100, v100
	v_exp_f32_e32 v101, v101
	v_exp_f32_e32 v102, v102
	v_exp_f32_e32 v103, v103
	v_exp_f32_e32 v104, v104
	v_exp_f32_e32 v105, v105
	v_add_f32_e32 v98, 1.0, v98
	v_add_f32_e32 v99, 1.0, v99
	v_add_f32_e32 v100, 1.0, v100
	v_add_f32_e32 v101, 1.0, v101
	v_add_f32_e32 v102, 1.0, v102
	v_add_f32_e32 v103, 1.0, v103
	v_add_f32_e32 v104, 1.0, v104
	v_add_f32_e32 v105, 1.0, v105
	v_rcp_f32_e32 v98, v98
	v_rcp_f32_e32 v99, v99
	v_rcp_f32_e32 v100, v100
	v_rcp_f32_e32 v101, v101
	v_rcp_f32_e32 v102, v102
	v_rcp_f32_e32 v104, v104
	v_rcp_f32_e32 v105, v105
	v_rcp_f32_e32 v103, v103
	v_pk_mul_f32 v[96:97], v[96:97], v[100:101]
	v_pk_mul_f32 v[94:95], v[94:95], v[98:99]
	v_pk_mul_f32 v[92:93], v[92:93], v[104:105]
	v_pk_mul_f32 v[90:91], v[90:91], v[102:103]
.LBB0_825:
	v_or_b32_e32 v98, 32, v148
	v_ashrrev_i32_e32 v99, 31, v98
	v_lshlrev_b64 v[98:99], 7, v[98:99]
	v_lshl_add_u64 v[98:99], v[150:151], 0, v[98:99]
	s_and_b64 vcc, exec, s[6:7]
	v_cvt_pk_bf16_f32 v94, v94, v95
	v_cvt_pk_bf16_f32 v95, v96, v97
	v_cvt_pk_bf16_f32 v96, v90, v91
	v_cvt_pk_bf16_f32 v97, v92, v93
	global_store_dwordx4 v[98:99], v[94:97], off sc0 sc1
	s_cbranch_vccnz .LBB0_827
	v_mul_f32_e32 v90, 0xbfb8aa3b, v86
	v_mul_f32_e32 v91, 0xbfb8aa3b, v87
	v_mul_f32_e32 v92, 0xbfb8aa3b, v88
	v_mul_f32_e32 v93, 0xbfb8aa3b, v89
	v_mul_f32_e32 v94, 0xbfb8aa3b, v82
	v_mul_f32_e32 v95, 0xbfb8aa3b, v83
	v_mul_f32_e32 v96, 0xbfb8aa3b, v84
	v_mul_f32_e32 v97, 0xbfb8aa3b, v85
	v_exp_f32_e32 v90, v90
	v_exp_f32_e32 v91, v91
	v_exp_f32_e32 v92, v92
	v_exp_f32_e32 v93, v93
	v_exp_f32_e32 v94, v94
	v_exp_f32_e32 v95, v95
	v_exp_f32_e32 v96, v96
	v_exp_f32_e32 v97, v97
	v_add_f32_e32 v90, 1.0, v90
	v_add_f32_e32 v91, 1.0, v91
	v_add_f32_e32 v92, 1.0, v92
	v_add_f32_e32 v93, 1.0, v93
	v_add_f32_e32 v94, 1.0, v94
	v_add_f32_e32 v95, 1.0, v95
	v_add_f32_e32 v96, 1.0, v96
	v_add_f32_e32 v97, 1.0, v97
	v_rcp_f32_e32 v90, v90
	v_rcp_f32_e32 v91, v91
	v_rcp_f32_e32 v92, v92
	v_rcp_f32_e32 v93, v93
	v_rcp_f32_e32 v94, v94
	v_rcp_f32_e32 v96, v96
	v_rcp_f32_e32 v97, v97
	v_rcp_f32_e32 v95, v95
	v_pk_mul_f32 v[88:89], v[88:89], v[92:93]
	v_pk_mul_f32 v[86:87], v[86:87], v[90:91]
	v_pk_mul_f32 v[84:85], v[84:85], v[96:97]
	v_pk_mul_f32 v[82:83], v[82:83], v[94:95]
.LBB0_827:
	v_cvt_pk_bf16_f32 v86, v86, v87
	v_cvt_pk_bf16_f32 v87, v88, v89
	s_nop 0
	v_cvt_pk_bf16_f32 v88, v82, v83
	v_add_co_u32_e32 v82, vcc, 0x840000, v98
	v_cvt_pk_bf16_f32 v89, v84, v85
	s_nop 1
	v_addc_co_u32_e32 v83, vcc, 0, v99, vcc
	s_and_b64 vcc, exec, s[6:7]
	global_store_dwordx4 v[82:83], v[86:89], off sc0 sc1
	s_cbranch_vccnz .LBB0_829
	v_mul_f32_e32 v82, 0xbfb8aa3b, v78
	v_mul_f32_e32 v83, 0xbfb8aa3b, v79
	v_mul_f32_e32 v84, 0xbfb8aa3b, v80
	v_mul_f32_e32 v85, 0xbfb8aa3b, v81
	v_mul_f32_e32 v86, 0xbfb8aa3b, v74
	v_mul_f32_e32 v87, 0xbfb8aa3b, v75
	v_mul_f32_e32 v88, 0xbfb8aa3b, v76
	v_mul_f32_e32 v89, 0xbfb8aa3b, v77
	v_exp_f32_e32 v82, v82
	v_exp_f32_e32 v83, v83
	v_exp_f32_e32 v84, v84
	v_exp_f32_e32 v85, v85
	v_exp_f32_e32 v86, v86
	v_exp_f32_e32 v87, v87
	v_exp_f32_e32 v88, v88
	v_exp_f32_e32 v89, v89
	v_add_f32_e32 v82, 1.0, v82
	v_add_f32_e32 v83, 1.0, v83
	v_add_f32_e32 v84, 1.0, v84
	v_add_f32_e32 v85, 1.0, v85
	v_add_f32_e32 v86, 1.0, v86
	v_add_f32_e32 v87, 1.0, v87
	v_add_f32_e32 v88, 1.0, v88
	v_add_f32_e32 v89, 1.0, v89
	v_rcp_f32_e32 v82, v82
	v_rcp_f32_e32 v83, v83
	v_rcp_f32_e32 v84, v84
	v_rcp_f32_e32 v85, v85
	v_rcp_f32_e32 v86, v86
	v_rcp_f32_e32 v88, v88
	v_rcp_f32_e32 v89, v89
	v_rcp_f32_e32 v87, v87
	v_pk_mul_f32 v[80:81], v[80:81], v[84:85]
	v_pk_mul_f32 v[78:79], v[78:79], v[82:83]
	v_pk_mul_f32 v[76:77], v[76:77], v[88:89]
	v_pk_mul_f32 v[74:75], v[74:75], v[86:87]
.LBB0_829:
	v_or_b32_e32 v82, 48, v148
	v_ashrrev_i32_e32 v83, 31, v82
	v_lshlrev_b64 v[82:83], 7, v[82:83]
	v_lshl_add_u64 v[82:83], v[150:151], 0, v[82:83]
	s_and_b64 vcc, exec, s[6:7]
	v_cvt_pk_bf16_f32 v78, v78, v79
	v_cvt_pk_bf16_f32 v79, v80, v81
	v_cvt_pk_bf16_f32 v80, v74, v75
	v_cvt_pk_bf16_f32 v81, v76, v77
	global_store_dwordx4 v[82:83], v[78:81], off sc0 sc1
	s_cbranch_vccnz .LBB0_831
	v_mul_f32_e32 v74, 0xbfb8aa3b, v70
	v_mul_f32_e32 v75, 0xbfb8aa3b, v71
	v_mul_f32_e32 v76, 0xbfb8aa3b, v72
	v_mul_f32_e32 v77, 0xbfb8aa3b, v73
	v_mul_f32_e32 v78, 0xbfb8aa3b, v66
	v_mul_f32_e32 v79, 0xbfb8aa3b, v67
	v_mul_f32_e32 v80, 0xbfb8aa3b, v68
	v_mul_f32_e32 v81, 0xbfb8aa3b, v69
	v_exp_f32_e32 v74, v74
	v_exp_f32_e32 v75, v75
	v_exp_f32_e32 v76, v76
	v_exp_f32_e32 v77, v77
	v_exp_f32_e32 v78, v78
	v_exp_f32_e32 v79, v79
	v_exp_f32_e32 v80, v80
	v_exp_f32_e32 v81, v81
	v_add_f32_e32 v74, 1.0, v74
	v_add_f32_e32 v75, 1.0, v75
	v_add_f32_e32 v76, 1.0, v76
	v_add_f32_e32 v77, 1.0, v77
	v_add_f32_e32 v78, 1.0, v78
	v_add_f32_e32 v79, 1.0, v79
	v_add_f32_e32 v80, 1.0, v80
	v_add_f32_e32 v81, 1.0, v81
	v_rcp_f32_e32 v74, v74
	v_rcp_f32_e32 v75, v75
	v_rcp_f32_e32 v76, v76
	v_rcp_f32_e32 v77, v77
	v_rcp_f32_e32 v78, v78
	v_rcp_f32_e32 v80, v80
	v_rcp_f32_e32 v81, v81
	v_rcp_f32_e32 v79, v79
	v_pk_mul_f32 v[72:73], v[72:73], v[76:77]
	v_pk_mul_f32 v[70:71], v[70:71], v[74:75]
	v_pk_mul_f32 v[68:69], v[68:69], v[80:81]
	v_pk_mul_f32 v[66:67], v[66:67], v[78:79]
.LBB0_831:
	v_cvt_pk_bf16_f32 v70, v70, v71
	v_cvt_pk_bf16_f32 v71, v72, v73
	s_nop 0
	v_cvt_pk_bf16_f32 v72, v66, v67
	v_add_co_u32_e32 v66, vcc, 0x840000, v82
	v_cvt_pk_bf16_f32 v73, v68, v69
	s_nop 1
	v_addc_co_u32_e32 v67, vcc, 0, v83, vcc
	s_and_b64 vcc, exec, s[6:7]
	global_store_dwordx4 v[66:67], v[70:73], off sc0 sc1
	s_cbranch_vccnz .LBB0_833
	v_mul_f32_e32 v66, 0xbfb8aa3b, v62
	v_mul_f32_e32 v67, 0xbfb8aa3b, v63
	v_mul_f32_e32 v68, 0xbfb8aa3b, v64
	v_mul_f32_e32 v69, 0xbfb8aa3b, v65
	v_mul_f32_e32 v70, 0xbfb8aa3b, v58
	v_mul_f32_e32 v71, 0xbfb8aa3b, v59
	v_mul_f32_e32 v72, 0xbfb8aa3b, v60
	v_mul_f32_e32 v73, 0xbfb8aa3b, v61
	v_exp_f32_e32 v66, v66
	v_exp_f32_e32 v67, v67
	v_exp_f32_e32 v68, v68
	v_exp_f32_e32 v69, v69
	v_exp_f32_e32 v70, v70
	v_exp_f32_e32 v71, v71
	v_exp_f32_e32 v72, v72
	v_exp_f32_e32 v73, v73
	v_add_f32_e32 v66, 1.0, v66
	v_add_f32_e32 v67, 1.0, v67
	v_add_f32_e32 v68, 1.0, v68
	v_add_f32_e32 v69, 1.0, v69
	v_add_f32_e32 v70, 1.0, v70
	v_add_f32_e32 v71, 1.0, v71
	v_add_f32_e32 v72, 1.0, v72
	v_add_f32_e32 v73, 1.0, v73
	v_rcp_f32_e32 v66, v66
	v_rcp_f32_e32 v67, v67
	v_rcp_f32_e32 v68, v68
	v_rcp_f32_e32 v69, v69
	v_rcp_f32_e32 v70, v70
	v_rcp_f32_e32 v72, v72
	v_rcp_f32_e32 v73, v73
	v_rcp_f32_e32 v71, v71
	v_pk_mul_f32 v[64:65], v[64:65], v[68:69]
	v_pk_mul_f32 v[62:63], v[62:63], v[66:67]
	v_pk_mul_f32 v[60:61], v[60:61], v[72:73]
	v_pk_mul_f32 v[58:59], v[58:59], v[70:71]
.LBB0_833:
	v_lshlrev_b64 v[66:67], 7, v[148:149]
	v_lshl_add_u64 v[66:67], v[150:151], 0, v[66:67]
	v_cvt_pk_bf16_f32 v62, v62, v63
	v_cvt_pk_bf16_f32 v63, v64, v65
	v_cvt_pk_bf16_f32 v64, v58, v59
	v_add_co_u32_e32 v58, vcc, 0x4000, v66
	v_cvt_pk_bf16_f32 v65, v60, v61
	s_nop 1
	v_addc_co_u32_e32 v59, vcc, 0, v67, vcc
	s_and_b64 vcc, exec, s[6:7]
	global_store_dwordx4 v[58:59], v[62:65], off sc0 sc1
	s_cbranch_vccnz .LBB0_835
	v_mul_f32_e32 v58, 0xbfb8aa3b, v54
	v_mul_f32_e32 v59, 0xbfb8aa3b, v55
	v_mul_f32_e32 v60, 0xbfb8aa3b, v56
	v_mul_f32_e32 v61, 0xbfb8aa3b, v57
	v_mul_f32_e32 v62, 0xbfb8aa3b, v50
	v_mul_f32_e32 v63, 0xbfb8aa3b, v51
	v_mul_f32_e32 v64, 0xbfb8aa3b, v52
	v_mul_f32_e32 v65, 0xbfb8aa3b, v53
	v_exp_f32_e32 v58, v58
	v_exp_f32_e32 v59, v59
	v_exp_f32_e32 v60, v60
	v_exp_f32_e32 v61, v61
	v_exp_f32_e32 v62, v62
	v_exp_f32_e32 v63, v63
	v_exp_f32_e32 v64, v64
	v_exp_f32_e32 v65, v65
	v_add_f32_e32 v58, 1.0, v58
	v_add_f32_e32 v59, 1.0, v59
	v_add_f32_e32 v60, 1.0, v60
	v_add_f32_e32 v61, 1.0, v61
	v_add_f32_e32 v62, 1.0, v62
	v_add_f32_e32 v63, 1.0, v63
	v_add_f32_e32 v64, 1.0, v64
	v_add_f32_e32 v65, 1.0, v65
	v_rcp_f32_e32 v58, v58
	v_rcp_f32_e32 v59, v59
	v_rcp_f32_e32 v60, v60
	v_rcp_f32_e32 v61, v61
	v_rcp_f32_e32 v62, v62
	v_rcp_f32_e32 v64, v64
	v_rcp_f32_e32 v65, v65
	v_rcp_f32_e32 v63, v63
	v_pk_mul_f32 v[56:57], v[56:57], v[60:61]
	v_pk_mul_f32 v[54:55], v[54:55], v[58:59]
	v_pk_mul_f32 v[52:53], v[52:53], v[64:65]
	v_pk_mul_f32 v[50:51], v[50:51], v[62:63]
.LBB0_835:
	v_lshl_add_u64 v[58:59], v[66:67], 0, s[16:17]
	v_cvt_pk_bf16_f32 v54, v54, v55
	v_cvt_pk_bf16_f32 v55, v56, v57
	v_cvt_pk_bf16_f32 v56, v50, v51
	v_add_co_u32_e32 v50, vcc, 0x840000, v58
	v_cvt_pk_bf16_f32 v57, v52, v53
	s_nop 1
	v_addc_co_u32_e32 v51, vcc, 0, v59, vcc
	s_and_b64 vcc, exec, s[6:7]
	global_store_dwordx4 v[50:51], v[54:57], off sc0 sc1
	s_cbranch_vccnz .LBB0_837
	v_mul_f32_e32 v50, 0xbfb8aa3b, v46
	v_mul_f32_e32 v51, 0xbfb8aa3b, v47
	v_mul_f32_e32 v52, 0xbfb8aa3b, v48
	v_mul_f32_e32 v53, 0xbfb8aa3b, v49
	v_mul_f32_e32 v54, 0xbfb8aa3b, v42
	v_mul_f32_e32 v55, 0xbfb8aa3b, v43
	v_mul_f32_e32 v56, 0xbfb8aa3b, v44
	v_mul_f32_e32 v57, 0xbfb8aa3b, v45
	v_exp_f32_e32 v50, v50
	v_exp_f32_e32 v51, v51
	v_exp_f32_e32 v52, v52
	v_exp_f32_e32 v53, v53
	v_exp_f32_e32 v54, v54
	v_exp_f32_e32 v55, v55
	v_exp_f32_e32 v56, v56
	v_exp_f32_e32 v57, v57
	v_add_f32_e32 v50, 1.0, v50
	v_add_f32_e32 v51, 1.0, v51
	v_add_f32_e32 v52, 1.0, v52
	v_add_f32_e32 v53, 1.0, v53
	v_add_f32_e32 v54, 1.0, v54
	v_add_f32_e32 v55, 1.0, v55
	v_add_f32_e32 v56, 1.0, v56
	v_add_f32_e32 v57, 1.0, v57
	v_rcp_f32_e32 v50, v50
	v_rcp_f32_e32 v51, v51
	v_rcp_f32_e32 v52, v52
	v_rcp_f32_e32 v53, v53
	v_rcp_f32_e32 v54, v54
	v_rcp_f32_e32 v56, v56
	v_rcp_f32_e32 v57, v57
	v_rcp_f32_e32 v55, v55
	v_pk_mul_f32 v[48:49], v[48:49], v[52:53]
	v_pk_mul_f32 v[46:47], v[46:47], v[50:51]
	v_pk_mul_f32 v[44:45], v[44:45], v[56:57]
	v_pk_mul_f32 v[42:43], v[42:43], v[54:55]
.LBB0_837:
	v_lshlrev_b64 v[50:51], 7, v[148:149]
	v_lshl_add_u64 v[50:51], v[150:151], 0, v[50:51]
	v_cvt_pk_bf16_f32 v46, v46, v47
	v_cvt_pk_bf16_f32 v47, v48, v49
	v_cvt_pk_bf16_f32 v48, v42, v43
	v_add_co_u32_e32 v42, vcc, 0x4000, v50
	v_cvt_pk_bf16_f32 v49, v44, v45
	s_nop 1
	v_addc_co_u32_e32 v43, vcc, 0, v51, vcc
	s_and_b64 vcc, exec, s[6:7]
	global_store_dwordx4 v[42:43], v[46:49], off offset:2048 sc0 sc1
	s_cbranch_vccnz .LBB0_839
	v_mul_f32_e32 v42, 0xbfb8aa3b, v38
	v_mul_f32_e32 v43, 0xbfb8aa3b, v39
	v_mul_f32_e32 v44, 0xbfb8aa3b, v40
	v_mul_f32_e32 v45, 0xbfb8aa3b, v41
	v_mul_f32_e32 v46, 0xbfb8aa3b, v34
	v_mul_f32_e32 v47, 0xbfb8aa3b, v35
	v_mul_f32_e32 v48, 0xbfb8aa3b, v36
	v_mul_f32_e32 v49, 0xbfb8aa3b, v37
	v_exp_f32_e32 v42, v42
	v_exp_f32_e32 v43, v43
	v_exp_f32_e32 v44, v44
	v_exp_f32_e32 v45, v45
	v_exp_f32_e32 v46, v46
	v_exp_f32_e32 v47, v47
	v_exp_f32_e32 v48, v48
	v_exp_f32_e32 v49, v49
	v_add_f32_e32 v42, 1.0, v42
	v_add_f32_e32 v43, 1.0, v43
	v_add_f32_e32 v44, 1.0, v44
	v_add_f32_e32 v45, 1.0, v45
	v_add_f32_e32 v46, 1.0, v46
	v_add_f32_e32 v47, 1.0, v47
	v_add_f32_e32 v48, 1.0, v48
	v_add_f32_e32 v49, 1.0, v49
	v_rcp_f32_e32 v42, v42
	v_rcp_f32_e32 v43, v43
	v_rcp_f32_e32 v44, v44
	v_rcp_f32_e32 v45, v45
	v_rcp_f32_e32 v46, v46
	v_rcp_f32_e32 v48, v48
	v_rcp_f32_e32 v49, v49
	v_rcp_f32_e32 v47, v47
	v_pk_mul_f32 v[40:41], v[40:41], v[44:45]
	v_pk_mul_f32 v[38:39], v[38:39], v[42:43]
	v_pk_mul_f32 v[36:37], v[36:37], v[48:49]
	v_pk_mul_f32 v[34:35], v[34:35], v[46:47]
.LBB0_839:
	v_lshl_add_u64 v[42:43], v[50:51], 0, s[18:19]
	v_cvt_pk_bf16_f32 v38, v38, v39
	v_cvt_pk_bf16_f32 v39, v40, v41
	v_cvt_pk_bf16_f32 v40, v34, v35
	v_add_co_u32_e32 v34, vcc, 0x840000, v42
	v_cvt_pk_bf16_f32 v41, v36, v37
	s_nop 1
	v_addc_co_u32_e32 v35, vcc, 0, v43, vcc
	s_and_b64 vcc, exec, s[6:7]
	global_store_dwordx4 v[34:35], v[38:41], off sc0 sc1
	s_cbranch_vccnz .LBB0_841
	v_mul_f32_e32 v34, 0xbfb8aa3b, v30
	v_mul_f32_e32 v35, 0xbfb8aa3b, v31
	v_mul_f32_e32 v36, 0xbfb8aa3b, v32
	v_mul_f32_e32 v37, 0xbfb8aa3b, v33
	v_mul_f32_e32 v38, 0xbfb8aa3b, v26
	v_mul_f32_e32 v39, 0xbfb8aa3b, v27
	v_mul_f32_e32 v40, 0xbfb8aa3b, v28
	v_mul_f32_e32 v41, 0xbfb8aa3b, v29
	v_exp_f32_e32 v34, v34
	v_exp_f32_e32 v35, v35
	v_exp_f32_e32 v36, v36
	v_exp_f32_e32 v37, v37
	v_exp_f32_e32 v38, v38
	v_exp_f32_e32 v39, v39
	v_exp_f32_e32 v40, v40
	v_exp_f32_e32 v41, v41
	v_add_f32_e32 v34, 1.0, v34
	v_add_f32_e32 v35, 1.0, v35
	v_add_f32_e32 v36, 1.0, v36
	v_add_f32_e32 v37, 1.0, v37
	v_add_f32_e32 v38, 1.0, v38
	v_add_f32_e32 v39, 1.0, v39
	v_add_f32_e32 v40, 1.0, v40
	v_add_f32_e32 v41, 1.0, v41
	v_rcp_f32_e32 v34, v34
	v_rcp_f32_e32 v35, v35
	v_rcp_f32_e32 v36, v36
	v_rcp_f32_e32 v37, v37
	v_rcp_f32_e32 v38, v38
	v_rcp_f32_e32 v40, v40
	v_rcp_f32_e32 v41, v41
	v_rcp_f32_e32 v39, v39
	v_pk_mul_f32 v[32:33], v[32:33], v[36:37]
	v_pk_mul_f32 v[30:31], v[30:31], v[34:35]
	v_pk_mul_f32 v[28:29], v[28:29], v[40:41]
	v_pk_mul_f32 v[26:27], v[26:27], v[38:39]
.LBB0_841:
	v_lshlrev_b64 v[34:35], 7, v[148:149]
	v_lshl_add_u64 v[34:35], v[150:151], 0, v[34:35]
	v_cvt_pk_bf16_f32 v30, v30, v31
	v_cvt_pk_bf16_f32 v31, v32, v33
	v_cvt_pk_bf16_f32 v32, v26, v27
	v_add_co_u32_e32 v26, vcc, 0x5000, v34
	v_cvt_pk_bf16_f32 v33, v28, v29
	s_nop 1
	v_addc_co_u32_e32 v27, vcc, 0, v35, vcc
	s_and_b64 vcc, exec, s[6:7]
	global_store_dwordx4 v[26:27], v[30:33], off sc0 sc1
	s_cbranch_vccnz .LBB0_843
	v_mul_f32_e32 v26, 0xbfb8aa3b, v22
	v_mul_f32_e32 v27, 0xbfb8aa3b, v23
	v_mul_f32_e32 v28, 0xbfb8aa3b, v24
	v_mul_f32_e32 v29, 0xbfb8aa3b, v25
	v_mul_f32_e32 v30, 0xbfb8aa3b, v18
	v_mul_f32_e32 v31, 0xbfb8aa3b, v19
	v_mul_f32_e32 v32, 0xbfb8aa3b, v20
	v_mul_f32_e32 v33, 0xbfb8aa3b, v21
	v_exp_f32_e32 v26, v26
	v_exp_f32_e32 v27, v27
	v_exp_f32_e32 v28, v28
	v_exp_f32_e32 v29, v29
	v_exp_f32_e32 v30, v30
	v_exp_f32_e32 v31, v31
	v_exp_f32_e32 v32, v32
	v_exp_f32_e32 v33, v33
	v_add_f32_e32 v26, 1.0, v26
	v_add_f32_e32 v27, 1.0, v27
	v_add_f32_e32 v28, 1.0, v28
	v_add_f32_e32 v29, 1.0, v29
	v_add_f32_e32 v30, 1.0, v30
	v_add_f32_e32 v31, 1.0, v31
	v_add_f32_e32 v32, 1.0, v32
	v_add_f32_e32 v33, 1.0, v33
	v_rcp_f32_e32 v26, v26
	v_rcp_f32_e32 v27, v27
	v_rcp_f32_e32 v28, v28
	v_rcp_f32_e32 v29, v29
	v_rcp_f32_e32 v30, v30
	v_rcp_f32_e32 v32, v32
	v_rcp_f32_e32 v33, v33
	v_rcp_f32_e32 v31, v31
	v_pk_mul_f32 v[24:25], v[24:25], v[28:29]
	v_pk_mul_f32 v[22:23], v[22:23], v[26:27]
	v_pk_mul_f32 v[20:21], v[20:21], v[32:33]
	v_pk_mul_f32 v[18:19], v[18:19], v[30:31]
.LBB0_843:
	v_lshl_add_u64 v[26:27], v[34:35], 0, s[20:21]
	v_cvt_pk_bf16_f32 v22, v22, v23
	v_cvt_pk_bf16_f32 v23, v24, v25
	v_cvt_pk_bf16_f32 v24, v18, v19
	v_add_co_u32_e32 v18, vcc, 0x840000, v26
	v_cvt_pk_bf16_f32 v25, v20, v21
	s_nop 1
	v_addc_co_u32_e32 v19, vcc, 0, v27, vcc
	s_and_b64 vcc, exec, s[6:7]
	global_store_dwordx4 v[18:19], v[22:25], off sc0 sc1
	s_cbranch_vccnz .LBB0_845
	v_mul_f32_e32 v18, 0xbfb8aa3b, v14
	v_mul_f32_e32 v19, 0xbfb8aa3b, v15
	v_mul_f32_e32 v20, 0xbfb8aa3b, v16
	v_mul_f32_e32 v21, 0xbfb8aa3b, v17
	v_mul_f32_e32 v22, 0xbfb8aa3b, v10
	v_mul_f32_e32 v23, 0xbfb8aa3b, v11
	v_mul_f32_e32 v24, 0xbfb8aa3b, v12
	v_mul_f32_e32 v25, 0xbfb8aa3b, v13
	v_exp_f32_e32 v18, v18
	v_exp_f32_e32 v19, v19
	v_exp_f32_e32 v20, v20
	v_exp_f32_e32 v21, v21
	v_exp_f32_e32 v22, v22
	v_exp_f32_e32 v23, v23
	v_exp_f32_e32 v24, v24
	v_exp_f32_e32 v25, v25
	v_add_f32_e32 v18, 1.0, v18
	v_add_f32_e32 v19, 1.0, v19
	v_add_f32_e32 v20, 1.0, v20
	v_add_f32_e32 v21, 1.0, v21
	v_add_f32_e32 v22, 1.0, v22
	v_add_f32_e32 v23, 1.0, v23
	v_add_f32_e32 v24, 1.0, v24
	v_add_f32_e32 v25, 1.0, v25
	v_rcp_f32_e32 v18, v18
	v_rcp_f32_e32 v19, v19
	v_rcp_f32_e32 v20, v20
	v_rcp_f32_e32 v21, v21
	v_rcp_f32_e32 v22, v22
	v_rcp_f32_e32 v24, v24
	v_rcp_f32_e32 v25, v25
	v_rcp_f32_e32 v23, v23
	v_pk_mul_f32 v[16:17], v[16:17], v[20:21]
	v_pk_mul_f32 v[14:15], v[14:15], v[18:19]
	v_pk_mul_f32 v[12:13], v[12:13], v[24:25]
	v_pk_mul_f32 v[10:11], v[10:11], v[22:23]
.LBB0_845:
	v_lshlrev_b64 v[18:19], 7, v[148:149]
	v_lshl_add_u64 v[18:19], v[150:151], 0, v[18:19]
	v_cvt_pk_bf16_f32 v14, v14, v15
	v_cvt_pk_bf16_f32 v15, v16, v17
	v_cvt_pk_bf16_f32 v16, v10, v11
	v_add_co_u32_e32 v10, vcc, 0x5000, v18
	v_cvt_pk_bf16_f32 v17, v12, v13
	s_nop 1
	v_addc_co_u32_e32 v11, vcc, 0, v19, vcc
	s_and_b64 vcc, exec, s[6:7]
	global_store_dwordx4 v[10:11], v[14:17], off offset:2048 sc0 sc1
	s_cbranch_vccnz .LBB0_806
	v_mul_f32_e32 v10, 0xbfb8aa3b, v6
	v_mul_f32_e32 v11, 0xbfb8aa3b, v7
	v_mul_f32_e32 v12, 0xbfb8aa3b, v8
	v_mul_f32_e32 v13, 0xbfb8aa3b, v9
	v_mul_f32_e32 v14, 0xbfb8aa3b, v2
	v_mul_f32_e32 v15, 0xbfb8aa3b, v3
	v_mul_f32_e32 v16, 0xbfb8aa3b, v4
	v_mul_f32_e32 v17, 0xbfb8aa3b, v5
	v_exp_f32_e32 v10, v10
	v_exp_f32_e32 v11, v11
	v_exp_f32_e32 v12, v12
	v_exp_f32_e32 v13, v13
	v_exp_f32_e32 v14, v14
	v_exp_f32_e32 v15, v15
	v_exp_f32_e32 v16, v16
	v_exp_f32_e32 v17, v17
	v_add_f32_e32 v10, 1.0, v10
	v_add_f32_e32 v11, 1.0, v11
	v_add_f32_e32 v12, 1.0, v12
	v_add_f32_e32 v13, 1.0, v13
	v_add_f32_e32 v14, 1.0, v14
	v_add_f32_e32 v15, 1.0, v15
	v_add_f32_e32 v16, 1.0, v16
	v_add_f32_e32 v17, 1.0, v17
	v_rcp_f32_e32 v10, v10
	v_rcp_f32_e32 v11, v11
	v_rcp_f32_e32 v12, v12
	v_rcp_f32_e32 v13, v13
	v_rcp_f32_e32 v14, v14
	v_rcp_f32_e32 v16, v16
	v_rcp_f32_e32 v17, v17
	v_rcp_f32_e32 v15, v15
	v_pk_mul_f32 v[8:9], v[8:9], v[12:13]
	v_pk_mul_f32 v[6:7], v[6:7], v[10:11]
	v_pk_mul_f32 v[4:5], v[4:5], v[16:17]
	v_pk_mul_f32 v[2:3], v[2:3], v[14:15]
	s_branch .LBB0_806

.LBB0_1000:
	v_lshl_add_u32 v146, s36, 8, v142
	v_lshl_or_b32 v140, s74, 8, v144
	v_ashrrev_i32_e32 v147, 31, v146
	v_ashrrev_i32_e32 v141, 31, v140
	v_lshlrev_b64 v[148:149], 11, v[146:147]
	v_lshl_add_u64 v[148:149], s[6:7], 0, v[148:149]
	v_lshlrev_b64 v[150:151], 1, v[140:141]
	v_lshl_add_u64 v[140:141], v[148:149], 0, v[150:151]
	v_cvt_pk_bf16_f32 v124, v124, v125
	v_cvt_pk_bf16_f32 v125, v126, v127
	v_cvt_pk_bf16_f32 v126, v120, v121
	v_cvt_pk_bf16_f32 v127, v122, v123
	global_store_dwordx4 v[140:141], v[124:127], off sc0 sc1
	v_cvt_pk_bf16_f32 v112, v112, v113
	v_cvt_pk_bf16_f32 v113, v114, v115
	v_cvt_pk_bf16_f32 v114, v104, v105
	v_or_b32_e32 v104, 16, v146
	v_ashrrev_i32_e32 v105, 31, v104
	v_lshlrev_b64 v[104:105], 11, v[104:105]
	v_lshl_add_u64 v[104:105], s[6:7], 0, v[104:105]
	v_cvt_pk_bf16_f32 v115, v106, v107
	global_store_dwordx4 v[140:141], v[112:115], off offset:256 sc0 sc1
	s_mov_b32 s74, s24
	s_mov_b32 s36, s26
	v_lshl_add_u64 v[112:113], v[104:105], 0, v[150:151]
	v_cvt_pk_bf16_f32 v104, v116, v117
	v_cvt_pk_bf16_f32 v105, v118, v119
	v_cvt_pk_bf16_f32 v106, v108, v109
	v_cvt_pk_bf16_f32 v107, v110, v111
	global_store_dwordx4 v[112:113], v[104:107], off sc0 sc1
	v_cvt_pk_bf16_f32 v96, v96, v97
	v_cvt_pk_bf16_f32 v97, v98, v99
	v_cvt_pk_bf16_f32 v98, v88, v89
	v_or_b32_e32 v88, 32, v146
	v_ashrrev_i32_e32 v89, 31, v88
	v_lshlrev_b64 v[88:89], 11, v[88:89]
	v_lshl_add_u64 v[88:89], s[6:7], 0, v[88:89]
	v_cvt_pk_bf16_f32 v99, v90, v91
	global_store_dwordx4 v[112:113], v[96:99], off offset:256 sc0 sc1
	s_mov_b64 s[38:39], s[30:31]
	s_mov_b64 s[40:41], s[28:29]
	v_lshl_add_u64 v[96:97], v[88:89], 0, v[150:151]
	v_cvt_pk_bf16_f32 v88, v100, v101
	v_cvt_pk_bf16_f32 v89, v102, v103
	v_cvt_pk_bf16_f32 v90, v92, v93
	v_cvt_pk_bf16_f32 v91, v94, v95
	global_store_dwordx4 v[96:97], v[88:91], off sc0 sc1
	v_cvt_pk_bf16_f32 v80, v80, v81
	v_cvt_pk_bf16_f32 v81, v82, v83
	v_cvt_pk_bf16_f32 v82, v72, v73
	v_or_b32_e32 v72, 48, v146
	v_ashrrev_i32_e32 v73, 31, v72
	v_lshlrev_b64 v[72:73], 11, v[72:73]
	v_lshl_add_u64 v[72:73], s[6:7], 0, v[72:73]
	v_cvt_pk_bf16_f32 v83, v74, v75
	global_store_dwordx4 v[96:97], v[80:83], off offset:256 sc0 sc1
	s_nop 1
	v_lshl_add_u64 v[80:81], v[72:73], 0, v[150:151]
	v_cvt_pk_bf16_f32 v72, v84, v85
	v_cvt_pk_bf16_f32 v73, v86, v87
	v_cvt_pk_bf16_f32 v74, v76, v77
	v_cvt_pk_bf16_f32 v75, v78, v79
	global_store_dwordx4 v[80:81], v[72:75], off sc0 sc1
	v_cvt_pk_bf16_f32 v68, v68, v69
	v_cvt_pk_bf16_f32 v69, v70, v71
	v_cvt_pk_bf16_f32 v70, v64, v65
	v_cvt_pk_bf16_f32 v71, v66, v67
	global_store_dwordx4 v[80:81], v[68:71], off offset:256 sc0 sc1
	v_cvt_pk_bf16_f32 v60, v60, v61
	v_cvt_pk_bf16_f32 v61, v62, v63
	v_cvt_pk_bf16_f32 v62, v56, v57
	v_add_co_u32_e32 v56, vcc, s68, v140
	v_lshl_add_u64 v[64:65], v[140:141], 0, s[12:13]
	s_nop 0
	v_addc_co_u32_e32 v57, vcc, 0, v141, vcc
	v_cvt_pk_bf16_f32 v63, v58, v59
	global_store_dwordx4 v[56:57], v[60:63], off sc0 sc1
	v_cvt_pk_bf16_f32 v48, v48, v49
	v_cvt_pk_bf16_f32 v49, v50, v51
	v_cvt_pk_bf16_f32 v50, v40, v41
	v_cvt_pk_bf16_f32 v51, v42, v43
	global_store_dwordx4 v[64:65], v[48:51], off offset:256 sc0 sc1
	v_cvt_pk_bf16_f32 v40, v52, v53
	v_cvt_pk_bf16_f32 v41, v54, v55
	v_cvt_pk_bf16_f32 v42, v44, v45
	v_add_co_u32_e32 v44, vcc, s69, v140
	s_nop 0
	v_lshl_add_u64 v[48:49], v[140:141], 0, s[16:17]
	v_addc_co_u32_e32 v45, vcc, 0, v141, vcc
	v_cvt_pk_bf16_f32 v43, v46, v47
	global_store_dwordx4 v[44:45], v[40:43], off sc0 sc1
	v_cvt_pk_bf16_f32 v32, v32, v33
	v_cvt_pk_bf16_f32 v33, v34, v35
	v_cvt_pk_bf16_f32 v34, v24, v25
	v_cvt_pk_bf16_f32 v35, v26, v27
	global_store_dwordx4 v[48:49], v[32:35], off offset:256 sc0 sc1
	v_cvt_pk_bf16_f32 v24, v36, v37
	v_cvt_pk_bf16_f32 v25, v38, v39
	v_cvt_pk_bf16_f32 v26, v28, v29
	v_add_co_u32_e32 v28, vcc, s72, v140
	s_nop 0
	v_lshl_add_u64 v[32:33], v[140:141], 0, s[18:19]
	v_addc_co_u32_e32 v29, vcc, 0, v141, vcc
	v_cvt_pk_bf16_f32 v27, v30, v31
	global_store_dwordx4 v[28:29], v[24:27], off sc0 sc1
	v_cvt_pk_bf16_f32 v16, v16, v17
	v_cvt_pk_bf16_f32 v17, v18, v19
	v_cvt_pk_bf16_f32 v18, v8, v9
	v_cvt_pk_bf16_f32 v19, v10, v11
	global_store_dwordx4 v[32:33], v[16:19], off offset:256 sc0 sc1
	v_cvt_pk_bf16_f32 v8, v20, v21
	v_cvt_pk_bf16_f32 v9, v22, v23
	v_cvt_pk_bf16_f32 v10, v12, v13
	v_add_co_u32_e32 v12, vcc, s73, v140
	s_nop 0
	v_lshl_add_u64 v[16:17], v[140:141], 0, s[20:21]
	v_addc_co_u32_e32 v13, vcc, 0, v141, vcc
	s_and_b64 vcc, exec, s[4:5]
	v_cvt_pk_bf16_f32 v11, v14, v15
	global_store_dwordx4 v[12:13], v[8:11], off sc0 sc1
	v_cvt_pk_bf16_f32 v4, v4, v5
	v_cvt_pk_bf16_f32 v5, v6, v7
	v_cvt_pk_bf16_f32 v6, v0, v1
	v_cvt_pk_bf16_f32 v7, v2, v3
	global_store_dwordx4 v[16:17], v[4:7], off offset:256 sc0 sc1
	s_cbranch_vccnz .LBB0_1011
